# GEMM tile loops: the two barriers at the end of each tile removed (last k-tile sits in LDS stage 1; the next tile's prologue writes only stage 0 and has its own barrier)
# baseline (speedup 1.0000x reference)
; __device__ __forceinline__ unsigned char* WS(const Params& p) { unsigned z = 0; asm volatile("" : "+s"(z)); return p.ws + z; }
; __device__ __forceinline__ void run_phase(const Params& p, int ph, char* lds, int mode) {
;     ...
;     case 6: {
;       for (int it = B; it < 1024; it += G) { if (EN(60)) gemm_RES((const bf16_t*)(WS(p) + OFF_U), DFF, (const bf16_t*)(WS(p) + OFF_WDN), p.out, p.out, (bf16_t*)(WS(p) + OFF_XB), (float*)(WS(p) + OFF_RSS), it, lds); __syncthreads(); }
;     } break;
.LBB0_93:
	s_or_b64 exec, exec, s[26:27]
	s_add_i32 s36, s36, s77
	s_add_i32 s35, s35, s30
	s_add_i32 s34, s34, s31
	s_cmpk_gt_i32 s36, 0x3ff
	s_waitcnt lgkmcnt(0)
	s_cbranch_scc1 .LBB0_104

; __device__ __forceinline__ void gemm_mainloop_d(const bf16_t* __restrict__ Ap, int lda, const bf16_t* __restrict__ Bt, int K,
;                                                 int m0, int n0, f32x4 (&acc)[4][4], char* lds) {
;     ...
;   for (int kt = 0; kt < nk; kt++) {
;     const int st = kt & 1;
;     if (kt + 1 < nk) dma(kt + 1, st ^ 1);
;     const char* la = lds + st * 32768; const char* lb = la + 16384;
;     bf16x8 af[2][4], bfv[2][4];
; #pragma unroll
;     for (int kc = 0; kc < 2; kc++) {
; #pragma unroll
;       for (int m = 0; m < 4; m++) { const int row = wr * 64 + m * 16 + fr; af[kc][m] = *(const bf16x8*)(la + (row * 8 + ((kc * 4 + fq) ^ ((row >> 1) & 7))) * 16); }
; #pragma unroll
;       for (int n = 0; n < 4; n++) { const int row = wc * 64 + n * 16 + fr; bfv[kc][n] = *(const bf16x8*)(lb + (row * 8 + ((kc * 4 + fq) ^ ((row >> 1) & 7))) * 16); }
;     }
;     __builtin_amdgcn_s_setprio(1);
; #pragma unroll
;     for (int kc = 0; kc < 2; kc++)
; #pragma unroll
;       for (int m = 0; m < 4; m++)
; #pragma unroll
;         for (int n = 0; n < 4; n++) acc[m][n] = __builtin_amdgcn_mfma_f32_16x16x32_bf16(bfv[kc][n], af[kc][m], acc[m][n], 0, 0, 0);
;     __builtin_amdgcn_s_setprio(0);
;     asm volatile("s_waitcnt vmcnt(0) lgkmcnt(0)" ::: "memory"); __builtin_amdgcn_s_barrier(); asm volatile("" ::: "memory");
;   }
.LBB0_95:
	s_setprio 3
	s_and_b32 s29, s26, 0x8000
	s_xor_b32 s37, s29, 0x8000
	s_add_i32 s37, s37, vcc_hi
	s_mov_b32 m0, s37
	s_add_i32 vcc_lo, s37, 0x4000
	global_load_lds_dwordx4 v150, s[46:47]
	s_mov_b32 m0, vcc_lo
	s_add_i32 vcc_lo, s37, 0x1000
	global_load_lds_dwordx4 v151, s[46:47]
	s_mov_b32 m0, vcc_lo
	s_add_i32 vcc_lo, s37, 0x5000
	global_load_lds_dwordx4 v152, s[46:47]
	s_mov_b32 m0, vcc_lo
	s_add_i32 vcc_lo, s37, 0x2000
	global_load_lds_dwordx4 v153, s[46:47]
	s_mov_b32 m0, vcc_lo
	s_add_i32 vcc_lo, s37, 0x6000
	global_load_lds_dwordx4 v154, s[46:47]
	s_mov_b32 m0, vcc_lo
	s_add_i32 vcc_lo, s37, 0x3000
	global_load_lds_dwordx4 v155, s[46:47]
	s_mov_b32 m0, vcc_lo
	s_add_i32 vcc_lo, s37, 0x7000
	global_load_lds_dwordx4 v156, s[46:47]
	s_mov_b32 m0, vcc_lo
	s_nop 0
	global_load_lds_dwordx4 v157, s[46:47]
	v_add_u32_e32 v150, 0x80, v150
	v_add_u32_e32 v151, 0x80, v151
	v_add_u32_e32 v152, 0x80, v152
	v_add_u32_e32 v153, 0x80, v153
	v_add_u32_e32 v154, 0x80, v154
	v_add_u32_e32 v155, 0x80, v155
	v_add_u32_e32 v156, 0x80, v156
	v_add_u32_e32 v157, 0x80, v157
	v_add_u32_e32 v98, s29, v85
	v_add_u32_e32 v114, s29, v84
	v_add_u32_e32 v130, s29, v83
	v_add_u32_e32 v146, s29, v2
	ds_read_b128 v[86:89], v98
	ds_read_b128 v[90:93], v98 offset:2048
	ds_read_b128 v[94:97], v98 offset:4096
	ds_read_b128 v[98:101], v98 offset:6144
	ds_read_b128 v[102:105], v114 offset:16384
	ds_read_b128 v[106:109], v114 offset:18432
	ds_read_b128 v[110:113], v114 offset:20480
	ds_read_b128 v[114:117], v114 offset:22528
	ds_read_b128 v[118:121], v130
	ds_read_b128 v[122:125], v130 offset:2048
	ds_read_b128 v[126:129], v130 offset:4096
	ds_read_b128 v[130:133], v130 offset:6144
	ds_read_b128 v[134:137], v146 offset:16384
	ds_read_b128 v[138:141], v146 offset:18432
	ds_read_b128 v[142:145], v146 offset:20480
	ds_read_b128 v[146:149], v146 offset:22528
	s_setprio 1
	s_waitcnt lgkmcnt(0)
	v_mfma_f32_16x16x32_bf16 v[64:67], v[102:105], v[86:89], v[64:67]
	v_mfma_f32_16x16x32_bf16 v[60:63], v[106:109], v[86:89], v[60:63]
	v_mfma_f32_16x16x32_bf16 v[56:59], v[110:113], v[86:89], v[56:59]
	v_mfma_f32_16x16x32_bf16 v[52:55], v[114:117], v[86:89], v[52:55]
	v_mfma_f32_16x16x32_bf16 v[48:51], v[102:105], v[90:93], v[48:51]
	v_mfma_f32_16x16x32_bf16 v[44:47], v[106:109], v[90:93], v[44:47]
	v_mfma_f32_16x16x32_bf16 v[40:43], v[110:113], v[90:93], v[40:43]
	v_mfma_f32_16x16x32_bf16 v[36:39], v[114:117], v[90:93], v[36:39]
	v_mfma_f32_16x16x32_bf16 v[32:35], v[102:105], v[94:97], v[32:35]
	v_mfma_f32_16x16x32_bf16 v[28:31], v[106:109], v[94:97], v[28:31]
	v_mfma_f32_16x16x32_bf16 v[24:27], v[110:113], v[94:97], v[24:27]
	v_mfma_f32_16x16x32_bf16 v[20:23], v[114:117], v[94:97], v[20:23]
	v_mfma_f32_16x16x32_bf16 v[16:19], v[102:105], v[98:101], v[16:19]
	v_mfma_f32_16x16x32_bf16 v[12:15], v[106:109], v[98:101], v[12:15]
	v_mfma_f32_16x16x32_bf16 v[8:11], v[110:113], v[98:101], v[8:11]
	v_mfma_f32_16x16x32_bf16 v[4:7], v[114:117], v[98:101], v[4:7]
	v_mfma_f32_16x16x32_bf16 v[64:67], v[134:137], v[118:121], v[64:67]
	v_mfma_f32_16x16x32_bf16 v[60:63], v[138:141], v[118:121], v[60:63]
	v_mfma_f32_16x16x32_bf16 v[56:59], v[142:145], v[118:121], v[56:59]
	v_mfma_f32_16x16x32_bf16 v[52:55], v[146:149], v[118:121], v[52:55]
	v_mfma_f32_16x16x32_bf16 v[48:51], v[134:137], v[122:125], v[48:51]
	v_mfma_f32_16x16x32_bf16 v[44:47], v[138:141], v[122:125], v[44:47]
	v_mfma_f32_16x16x32_bf16 v[40:43], v[142:145], v[122:125], v[40:43]
	v_mfma_f32_16x16x32_bf16 v[36:39], v[146:149], v[122:125], v[36:39]
	v_mfma_f32_16x16x32_bf16 v[32:35], v[134:137], v[126:129], v[32:35]
	v_mfma_f32_16x16x32_bf16 v[28:31], v[138:141], v[126:129], v[28:31]
	v_mfma_f32_16x16x32_bf16 v[24:27], v[142:145], v[126:129], v[24:27]
	v_mfma_f32_16x16x32_bf16 v[20:23], v[146:149], v[126:129], v[20:23]
	v_mfma_f32_16x16x32_bf16 v[16:19], v[134:137], v[130:133], v[16:19]
	v_mfma_f32_16x16x32_bf16 v[12:15], v[138:141], v[130:133], v[12:15]
	v_mfma_f32_16x16x32_bf16 v[8:11], v[142:145], v[130:133], v[8:11]
	v_mfma_f32_16x16x32_bf16 v[4:7], v[146:149], v[130:133], v[4:7]
	s_setprio 0
	s_waitcnt vmcnt(0) lgkmcnt(0)
	s_barrier
	s_add_u32 s24, s24, 0x80
	s_addc_u32 s25, s25, 0
	s_add_i32 s26, s26, 0x8000
	s_cmpk_eq_i32 s24, 0x1580
	s_cbranch_scc0 .LBB0_95
; __device__ __forceinline__ void gemm_mainloop_d(const bf16_t* __restrict__ Ap, int lda, const bf16_t* __restrict__ Bt, int K,
;                                                 int m0, int n0, f32x4 (&acc)[4][4], char* lds) {
;     ...
; #pragma unroll
;     for (int kc = 0; kc < 2; kc++)
; #pragma unroll
;       for (int m = 0; m < 4; m++)
; #pragma unroll
;         for (int n = 0; n < 4; n++) acc[m][n] = __builtin_amdgcn_mfma_f32_16x16x32_bf16(bfv[kc][n], af[kc][m], acc[m][n], 0, 0, 0);
;     __builtin_amdgcn_s_setprio(0);
;     asm volatile("s_waitcnt vmcnt(0) lgkmcnt(0)" ::: "memory"); __builtin_amdgcn_s_barrier(); asm volatile("" ::: "memory");
; __device__ __forceinline__ void gemm_RES(const bf16_t* A, int K, const bf16_t* Bt, const float* xin, float* xout, bf16_t* xb, float* rss, int item, char* lds) {
;     ...
; #pragma unroll
;   for (int m = 0; m < 4; m++) {
;     const int rowg = m0 + wr * 64 + m * 16 + fr;
;     const size_t ro = (size_t)rowg * DM;
	v_add_u32_e32 v0, 0, v85
	ds_read_b128 v[68:71], v0 offset:32768
	ds_read_b128 v[72:75], v0 offset:34816
	ds_read_b128 v[76:79], v0 offset:36864
	ds_read_b128 v[86:89], v0 offset:38912
	v_add_u32_e32 v0, 0, v84
	ds_read_b128 v[90:93], v0 offset:49152
	ds_read_b128 v[94:97], v0 offset:51200
	ds_read_b128 v[98:101], v0 offset:53248
	ds_read_b128 v[102:105], v0 offset:55296
	v_add_u32_e32 v0, 0, v83
	s_add_u32 s24, s46, s27
	ds_read_b128 v[80:83], v0 offset:32768
	ds_read_b128 v[106:109], v0 offset:34816
	ds_read_b128 v[110:113], v0 offset:36864
	ds_read_b128 v[114:117], v0 offset:38912
	v_add_u32_e32 v0, 0, v2
	s_addc_u32 s25, s47, 0
	ds_read_b128 v[118:121], v0 offset:49152
	ds_read_b128 v[122:125], v0 offset:51200
	ds_read_b128 v[126:129], v0 offset:53248
	ds_read_b128 v[130:133], v0 offset:55296
	s_add_u32 s28, s46, s28
	s_addc_u32 s29, s47, 0
	s_add_u32 s26, s24, 0x65a8000
	s_addc_u32 s27, s25, 0
	s_add_u32 s24, s28, 0xff8c000
	s_addc_u32 s25, s29, 0
	s_setprio 1
	s_waitcnt lgkmcnt(0)
	v_mfma_f32_16x16x32_bf16 v[56:59], v[98:101], v[68:71], v[56:59]
	v_mfma_f32_16x16x32_bf16 v[48:51], v[90:93], v[72:75], v[48:51]
	v_mfma_f32_16x16x32_bf16 v[44:47], v[94:97], v[72:75], v[44:47]
	v_mfma_f32_16x16x32_bf16 v[40:43], v[98:101], v[72:75], v[40:43]
	v_mfma_f32_16x16x32_bf16 v[36:39], v[102:105], v[72:75], v[36:39]
	v_mfma_f32_16x16x32_bf16 v[32:35], v[90:93], v[76:79], v[32:35]
	v_mfma_f32_16x16x32_bf16 v[28:31], v[94:97], v[76:79], v[28:31]
	v_mfma_f32_16x16x32_bf16 v[24:27], v[98:101], v[76:79], v[24:27]
	v_mfma_f32_16x16x32_bf16 v[20:23], v[102:105], v[76:79], v[20:23]
	v_mfma_f32_16x16x32_bf16 v[16:19], v[90:93], v[86:89], v[16:19]
	v_mfma_f32_16x16x32_bf16 v[12:15], v[94:97], v[86:89], v[12:15]
	v_mfma_f32_16x16x32_bf16 v[8:11], v[98:101], v[86:89], v[8:11]
	v_mfma_f32_16x16x32_bf16 v[4:7], v[102:105], v[86:89], v[4:7]
	v_mfma_f32_16x16x32_bf16 v[64:67], v[90:93], v[68:71], v[64:67]
	v_mfma_f32_16x16x32_bf16 v[60:63], v[94:97], v[68:71], v[60:63]
	v_mfma_f32_16x16x32_bf16 v[52:55], v[102:105], v[68:71], v[52:55]
	v_mfma_f32_16x16x32_bf16 v[56:59], v[126:129], v[80:83], v[56:59]
	v_mfma_f32_16x16x32_bf16 v[48:51], v[118:121], v[106:109], v[48:51]
	v_mfma_f32_16x16x32_bf16 v[44:47], v[122:125], v[106:109], v[44:47]
	v_mfma_f32_16x16x32_bf16 v[40:43], v[126:129], v[106:109], v[40:43]
	v_mfma_f32_16x16x32_bf16 v[36:39], v[130:133], v[106:109], v[36:39]
	v_mfma_f32_16x16x32_bf16 v[32:35], v[118:121], v[110:113], v[32:35]
	v_mfma_f32_16x16x32_bf16 v[28:31], v[122:125], v[110:113], v[28:31]
	v_mfma_f32_16x16x32_bf16 v[24:27], v[126:129], v[110:113], v[24:27]
	v_mfma_f32_16x16x32_bf16 v[20:23], v[130:133], v[110:113], v[20:23]
	v_mfma_f32_16x16x32_bf16 v[16:19], v[118:121], v[114:117], v[16:19]
	v_mfma_f32_16x16x32_bf16 v[12:15], v[122:125], v[114:117], v[12:15]
	v_mfma_f32_16x16x32_bf16 v[8:11], v[126:129], v[114:117], v[8:11]
	v_mfma_f32_16x16x32_bf16 v[4:7], v[130:133], v[114:117], v[4:7]
	v_mfma_f32_16x16x32_bf16 v[64:67], v[118:121], v[80:83], v[64:67]
	v_mfma_f32_16x16x32_bf16 v[60:63], v[122:125], v[80:83], v[60:63]
	v_mfma_f32_16x16x32_bf16 v[68:71], v[130:133], v[80:83], v[52:55]
	s_setprio 0
	v_mov_b32_e32 v0, v198
	s_waitcnt vmcnt(0) lgkmcnt(0)
; __device__ __forceinline__ unsigned pk2(float lo, float hi) { unsigned r; asm("v_cvt_pk_bf16_f32 %0, %1, %2" : "=v"(r) : "v"(lo), "v"(hi)); return r; }
; __device__ __forceinline__ float bflo(unsigned u) { return __uint_as_float(u << 16); }
; __device__ __forceinline__ float bfhi(unsigned u) { return __uint_as_float(u & 0xffff0000u); }
; __device__ __forceinline__ void gemm_RES(const bf16_t* A, int K, const bf16_t* Bt, const float* xin, float* xout, bf16_t* xb, float* rss, int item, char* lds) {
;     ...
; #pragma unroll
;   for (int m = 0; m < 4; m++) {
;     const int rowg = m0 + wr * 64 + m * 16 + fr;
;     const size_t ro = (size_t)rowg * DM;
;     float sq = 0.f;
; #pragma unroll
;     for (int n = 0; n < 4; n++) {
;       const int col = n0 + wc * 64 + n * 16 + fq * 4;
;       f32x4 xv = *(const f32x4*)(xin + ro + col);
;       const f32x4 xn = xv + acc[m][n];
;       *(f32x4*)(xout + ro + col) = xn;
;       u32x2 w; w[0] = pk2(xn[0], xn[1]); w[1] = pk2(xn[2], xn[3]); *(u32x2*)(xb + ro + col) = w;
;       const float b0 = bflo(w[0]), b1 = bfhi(w[0]), b2 = bflo(w[1]), b3 = bfhi(w[1]);
;       sq += b0 * b0 + b1 * b1 + b2 * b2 + b3 * b3;
;     }
;     sq += __shfl_xor(sq, 16); sq += __shfl_xor(sq, 32);
;     if (fq == 0) unsafeAtomicAdd(rss + rowg, sq);
	v_readlane_b32 s4, v252, 35
	v_ashrrev_i32_e32 v2, 1, v0
	v_and_b32_e32 v2, 0xffffffc0, v2
	v_bfe_u32 v80, v0, 4, 2
	v_add_u32_e32 v2, s3, v2
	v_and_b32_e32 v1, 64, v0
	v_and_or_b32 v0, v0, 15, v2
	v_lshlrev_b32_e32 v2, 2, v80
	v_or3_b32 v54, v2, v1, s2
	v_ashrrev_i32_e32 v1, 31, v0
	v_lshlrev_b64 v[52:53], 12, v[0:1]
	v_readlane_b32 s18, v252, 49
	v_readlane_b32 s19, v252, 50
	v_lshlrev_b32_e32 v2, 2, v54
	v_readlane_b32 s5, v252, 36
	v_lshl_add_u64 v[52:53], s[18:19], 0, v[52:53]
	v_lshl_add_u64 v[76:77], v[52:53], 0, v[2:3]
	global_load_dwordx4 v[72:75], v[76:77], off
	v_lshlrev_b32_e32 v52, 1, v54
	v_lshlrev_b64 v[54:55], 11, v[0:1]
	v_mov_b32_e32 v53, v3
	v_lshl_add_u64 v[54:55], s[26:27], 0, v[54:55]
	v_lshl_add_u64 v[78:79], v[54:55], 0, v[52:53]
	v_readlane_b32 s6, v252, 37
	v_readlane_b32 s7, v252, 38
	v_readlane_b32 s8, v252, 39
	v_readlane_b32 s9, v252, 40
	v_readlane_b32 s10, v252, 41
	v_readlane_b32 s11, v252, 42
	v_readlane_b32 s12, v252, 43
	v_readlane_b32 s13, v252, 44
	v_readlane_b32 s14, v252, 45
	v_readlane_b32 s15, v252, 46
	v_readlane_b32 s16, v252, 47
	v_readlane_b32 s17, v252, 48
	s_waitcnt vmcnt(0)
	v_pk_add_f32 v[66:67], v[66:67], v[74:75]
	v_pk_add_f32 v[64:65], v[64:65], v[72:73]
	global_store_dwordx4 v[76:77], v[64:67], off
	v_cvt_pk_bf16_f32 v54, v64, v65
	v_cvt_pk_bf16_f32 v55, v66, v67
	global_store_dwordx2 v[78:79], v[54:55], off
	global_load_dwordx4 v[64:67], v[76:77], off offset:64
	s_waitcnt vmcnt(0)
	v_pk_add_f32 v[62:63], v[62:63], v[66:67]
	v_pk_add_f32 v[60:61], v[60:61], v[64:65]
	global_store_dwordx4 v[76:77], v[60:63], off offset:64
	v_cvt_pk_bf16_f32 v64, v60, v61
	v_cvt_pk_bf16_f32 v65, v62, v63
	global_store_dwordx2 v[78:79], v[64:65], off offset:32
	global_load_dwordx4 v[60:63], v[76:77], off offset:128
	v_lshlrev_b32_e32 v66, 16, v54
	v_and_b32_e32 v54, 0xffff0000, v54
	v_mul_f32_e32 v54, v54, v54
	v_lshlrev_b32_e32 v67, 16, v55
	v_fmac_f32_e32 v54, v66, v66
	v_and_b32_e32 v55, 0xffff0000, v55
	v_fmac_f32_e32 v54, v67, v67
	v_fmac_f32_e32 v54, v55, v55
	v_lshlrev_b32_e32 v55, 16, v64
	v_and_b32_e32 v64, 0xffff0000, v64
	v_mul_f32_e32 v64, v64, v64
	v_lshlrev_b32_e32 v66, 16, v65
	v_fmac_f32_e32 v64, v55, v55
	v_and_b32_e32 v65, 0xffff0000, v65
	v_fmac_f32_e32 v64, v66, v66
	v_fmac_f32_e32 v64, v65, v65
	v_add_f32_e32 v54, v54, v64
	s_waitcnt vmcnt(0)
	v_pk_add_f32 v[58:59], v[58:59], v[62:63]
	v_pk_add_f32 v[56:57], v[56:57], v[60:61]
	global_store_dwordx4 v[76:77], v[56:59], off offset:128
	v_cvt_pk_bf16_f32 v62, v56, v57
	v_cvt_pk_bf16_f32 v63, v58, v59
	global_store_dwordx2 v[78:79], v[62:63], off offset:64
	global_load_dwordx4 v[58:61], v[76:77], off offset:192
	v_lshlrev_b32_e32 v55, 16, v62
	v_and_b32_e32 v62, 0xffff0000, v62
	v_mul_f32_e32 v62, v62, v62
	v_lshlrev_b32_e32 v64, 16, v63
	v_fmac_f32_e32 v62, v55, v55
	v_and_b32_e32 v63, 0xffff0000, v63
	v_fmac_f32_e32 v62, v64, v64
	v_fmac_f32_e32 v62, v63, v63
	v_add_f32_e32 v54, v54, v62
	v_and_b32_e32 v57, 64, v218
	v_xor_b32_e32 v56, 16, v218
	v_add_u32_e32 v57, 64, v57
	v_cmp_lt_i32_e32 vcc, v56, v57
	s_waitcnt vmcnt(0)
	v_pk_add_f32 v[58:59], v[68:69], v[58:59]
	s_nop 0
	v_cvt_pk_bf16_f32 v62, v58, v59
	v_pk_add_f32 v[60:61], v[70:71], v[60:61]
	v_and_b32_e32 v64, 0xffff0000, v62
	v_lshlrev_b32_e32 v55, 16, v62
	v_mul_f32_e32 v64, v64, v64
	v_cvt_pk_bf16_f32 v63, v60, v61
	v_fmac_f32_e32 v64, v55, v55
	v_lshlrev_b32_e32 v65, 16, v63
	v_and_b32_e32 v66, 0xffff0000, v63
	v_fmac_f32_e32 v64, v65, v65
	v_cndmask_b32_e32 v56, v218, v56, vcc
	v_fmac_f32_e32 v64, v66, v66
	v_lshlrev_b32_e32 v56, 2, v56
	v_add_f32_e32 v54, v54, v64
	ds_bpermute_b32 v55, v56, v54
	v_xor_b32_e32 v64, 32, v218
	v_cmp_lt_i32_e32 vcc, v64, v57
	global_store_dwordx4 v[76:77], v[58:61], off offset:192
	global_store_dwordx2 v[78:79], v[62:63], off offset:96
	v_cndmask_b32_e32 v57, v218, v64, vcc
	s_waitcnt lgkmcnt(0)
	v_add_f32_e32 v54, v54, v55
	v_lshlrev_b32_e32 v57, 2, v57
	ds_bpermute_b32 v55, v57, v54
	v_cmp_eq_u32_e32 vcc, 0, v80
	s_and_saveexec_b64 s[28:29], vcc
	s_cbranch_execz .LBB0_98
	v_lshl_add_u64 v[58:59], v[0:1], 2, s[24:25]
	s_waitcnt lgkmcnt(0)
	v_add_f32_e32 v1, v54, v55
	global_atomic_add_f32 v[58:59], v1, off

; __device__ __forceinline__ void gemm_mainloop_d(const bf16_t* __restrict__ Ap, int lda, const bf16_t* __restrict__ Bt, int K,
;                                                 int m0, int n0, f32x4 (&acc)[4][4], char* lds) {
;     ...
;   for (int kt = 0; kt < nk; kt++) {
;     const int st = kt & 1;
;     if (kt + 1 < nk) dma(kt + 1, st ^ 1);
;     const char* la = lds + st * 32768; const char* lb = la + 16384;
;     bf16x8 af[2][4], bfv[2][4];
; #pragma unroll
;     for (int kc = 0; kc < 2; kc++) {
; #pragma unroll
;       for (int m = 0; m < 4; m++) { const int row = wr * 64 + m * 16 + fr; af[kc][m] = *(const bf16x8*)(la + (row * 8 + ((kc * 4 + fq) ^ ((row >> 1) & 7))) * 16); }
; #pragma unroll
;       for (int n = 0; n < 4; n++) { const int row = wc * 64 + n * 16 + fr; bfv[kc][n] = *(const bf16x8*)(lb + (row * 8 + ((kc * 4 + fq) ^ ((row >> 1) & 7))) * 16); }
;     }
;     __builtin_amdgcn_s_setprio(1);
; #pragma unroll
;     for (int kc = 0; kc < 2; kc++)
; #pragma unroll
;       for (int m = 0; m < 4; m++)
; #pragma unroll
;         for (int n = 0; n < 4; n++) acc[m][n] = __builtin_amdgcn_mfma_f32_16x16x32_bf16(bfv[kc][n], af[kc][m], acc[m][n], 0, 0, 0);
;     __builtin_amdgcn_s_setprio(0);
;     asm volatile("s_waitcnt vmcnt(0) lgkmcnt(0)" ::: "memory"); __builtin_amdgcn_s_barrier(); asm volatile("" ::: "memory");
;   }
.LBB0_109:
	s_setprio 3
	s_and_b32 s34, s25, 0x8000
	s_xor_b32 s35, s34, 0x8000
	s_add_i32 s35, s35, vcc_hi
	s_mov_b32 m0, s35
	s_add_i32 vcc_lo, s35, 0x4000
	global_load_lds_dwordx4 v150, s[46:47]
	s_mov_b32 m0, vcc_lo
	s_add_i32 vcc_lo, s35, 0x1000
	global_load_lds_dwordx4 v151, s[46:47]
	s_mov_b32 m0, vcc_lo
	s_add_i32 vcc_lo, s35, 0x5000
	global_load_lds_dwordx4 v152, s[46:47]
	s_mov_b32 m0, vcc_lo
	s_add_i32 vcc_lo, s35, 0x2000
	global_load_lds_dwordx4 v153, s[46:47]
	s_mov_b32 m0, vcc_lo
	s_add_i32 vcc_lo, s35, 0x6000
	global_load_lds_dwordx4 v154, s[46:47]
	s_mov_b32 m0, vcc_lo
	s_add_i32 vcc_lo, s35, 0x3000
	global_load_lds_dwordx4 v155, s[46:47]
	s_mov_b32 m0, vcc_lo
	s_add_i32 vcc_lo, s35, 0x7000
	global_load_lds_dwordx4 v156, s[46:47]
	s_mov_b32 m0, vcc_lo
	s_nop 0
	global_load_lds_dwordx4 v157, s[46:47]
	v_add_u32_e32 v150, 0x80, v150
	v_add_u32_e32 v151, 0x80, v151
	v_add_u32_e32 v152, 0x80, v152
	v_add_u32_e32 v153, 0x80, v153
	v_add_u32_e32 v154, 0x80, v154
	v_add_u32_e32 v155, 0x80, v155
	v_add_u32_e32 v156, 0x80, v156
	v_add_u32_e32 v157, 0x80, v157
	v_add_u32_e32 v98, s34, v85
	v_add_u32_e32 v114, s34, v84
	v_add_u32_e32 v130, s34, v83
	v_add_u32_e32 v146, s34, v2
	ds_read_b128 v[86:89], v98
	ds_read_b128 v[90:93], v98 offset:2048
	ds_read_b128 v[94:97], v98 offset:4096
	ds_read_b128 v[98:101], v98 offset:6144
	ds_read_b128 v[102:105], v114 offset:16384
	ds_read_b128 v[106:109], v114 offset:18432
	ds_read_b128 v[110:113], v114 offset:20480
	ds_read_b128 v[114:117], v114 offset:22528
	ds_read_b128 v[118:121], v130
	ds_read_b128 v[122:125], v130 offset:2048
	ds_read_b128 v[126:129], v130 offset:4096
	ds_read_b128 v[130:133], v130 offset:6144
	ds_read_b128 v[134:137], v146 offset:16384
	ds_read_b128 v[138:141], v146 offset:18432
	ds_read_b128 v[142:145], v146 offset:20480
	ds_read_b128 v[146:149], v146 offset:22528
	s_setprio 1
	s_waitcnt lgkmcnt(0)
	v_mfma_f32_16x16x32_bf16 v[64:67], v[102:105], v[86:89], v[64:67]
	v_mfma_f32_16x16x32_bf16 v[60:63], v[106:109], v[86:89], v[60:63]
	v_mfma_f32_16x16x32_bf16 v[56:59], v[110:113], v[86:89], v[56:59]
	v_mfma_f32_16x16x32_bf16 v[52:55], v[114:117], v[86:89], v[52:55]
	v_mfma_f32_16x16x32_bf16 v[48:51], v[102:105], v[90:93], v[48:51]
	v_mfma_f32_16x16x32_bf16 v[44:47], v[106:109], v[90:93], v[44:47]
	v_mfma_f32_16x16x32_bf16 v[40:43], v[110:113], v[90:93], v[40:43]
	v_mfma_f32_16x16x32_bf16 v[36:39], v[114:117], v[90:93], v[36:39]
	v_mfma_f32_16x16x32_bf16 v[32:35], v[102:105], v[94:97], v[32:35]
	v_mfma_f32_16x16x32_bf16 v[28:31], v[106:109], v[94:97], v[28:31]
	v_mfma_f32_16x16x32_bf16 v[24:27], v[110:113], v[94:97], v[24:27]
	v_mfma_f32_16x16x32_bf16 v[20:23], v[114:117], v[94:97], v[20:23]
	v_mfma_f32_16x16x32_bf16 v[16:19], v[102:105], v[98:101], v[16:19]
	v_mfma_f32_16x16x32_bf16 v[12:15], v[106:109], v[98:101], v[12:15]
	v_mfma_f32_16x16x32_bf16 v[8:11], v[110:113], v[98:101], v[8:11]
	v_mfma_f32_16x16x32_bf16 v[4:7], v[114:117], v[98:101], v[4:7]
	v_mfma_f32_16x16x32_bf16 v[64:67], v[134:137], v[118:121], v[64:67]
	v_mfma_f32_16x16x32_bf16 v[60:63], v[138:141], v[118:121], v[60:63]
	v_mfma_f32_16x16x32_bf16 v[56:59], v[142:145], v[118:121], v[56:59]
	v_mfma_f32_16x16x32_bf16 v[52:55], v[146:149], v[118:121], v[52:55]
	v_mfma_f32_16x16x32_bf16 v[48:51], v[134:137], v[122:125], v[48:51]
	v_mfma_f32_16x16x32_bf16 v[44:47], v[138:141], v[122:125], v[44:47]
	v_mfma_f32_16x16x32_bf16 v[40:43], v[142:145], v[122:125], v[40:43]
	v_mfma_f32_16x16x32_bf16 v[36:39], v[146:149], v[122:125], v[36:39]
	v_mfma_f32_16x16x32_bf16 v[32:35], v[134:137], v[126:129], v[32:35]
	v_mfma_f32_16x16x32_bf16 v[28:31], v[138:141], v[126:129], v[28:31]
	v_mfma_f32_16x16x32_bf16 v[24:27], v[142:145], v[126:129], v[24:27]
	v_mfma_f32_16x16x32_bf16 v[20:23], v[146:149], v[126:129], v[20:23]
	v_mfma_f32_16x16x32_bf16 v[16:19], v[134:137], v[130:133], v[16:19]
	v_mfma_f32_16x16x32_bf16 v[12:15], v[138:141], v[130:133], v[12:15]
	v_mfma_f32_16x16x32_bf16 v[8:11], v[142:145], v[130:133], v[8:11]
	v_mfma_f32_16x16x32_bf16 v[4:7], v[146:149], v[130:133], v[4:7]
	s_setprio 0
	s_waitcnt vmcnt(0) lgkmcnt(0)
	s_barrier
	s_add_u32 s26, s26, 0x80
	s_addc_u32 s27, s27, 0
	s_add_i32 s25, s25, 0x8000
	s_cmpk_lg_i32 s26, 0x780
	s_cbranch_scc1 .LBB0_109
; __device__ __forceinline__ unsigned char* WS(const Params& p) { unsigned z = 0; asm volatile("" : "+s"(z)); return p.ws + z; }
; __device__ __forceinline__ void gemm_mainloop_d(const bf16_t* __restrict__ Ap, int lda, const bf16_t* __restrict__ Bt, int K,
;                                                 int m0, int n0, f32x4 (&acc)[4][4], char* lds) {
;     ...
;   for (int kt = 0; kt < nk; kt++) {
;     const int st = kt & 1;
;     if (kt + 1 < nk) dma(kt + 1, st ^ 1);
;     const char* la = lds + st * 32768; const char* lb = la + 16384;
;     bf16x8 af[2][4], bfv[2][4];
; #pragma unroll
;     for (int kc = 0; kc < 2; kc++) {
; #pragma unroll
;       for (int m = 0; m < 4; m++) { const int row = wr * 64 + m * 16 + fr; af[kc][m] = *(const bf16x8*)(la + (row * 8 + ((kc * 4 + fq) ^ ((row >> 1) & 7))) * 16); }
; #pragma unroll
;       for (int n = 0; n < 4; n++) { const int row = wc * 64 + n * 16 + fr; bfv[kc][n] = *(const bf16x8*)(lb + (row * 8 + ((kc * 4 + fq) ^ ((row >> 1) & 7))) * 16); }
;     }
;     __builtin_amdgcn_s_setprio(1);
; #pragma unroll
;     for (int kc = 0; kc < 2; kc++)
; #pragma unroll
;       for (int m = 0; m < 4; m++)
; #pragma unroll
;         for (int n = 0; n < 4; n++) acc[m][n] = __builtin_amdgcn_mfma_f32_16x16x32_bf16(bfv[kc][n], af[kc][m], acc[m][n], 0, 0, 0);
;     __builtin_amdgcn_s_setprio(0);
;     asm volatile("s_waitcnt vmcnt(0) lgkmcnt(0)" ::: "memory"); __builtin_amdgcn_s_barrier(); asm volatile("" ::: "memory");
;   }
; __device__ __forceinline__ void gemm_GU(const Params& p, int item, char* lds) {
;     ...
;   const float* rssg = (const float*)(WS(p) + OFF_RSS) + T + m0;
;   bf16_t* U = (bf16_t*)(WS(p) + OFF_U);
; #pragma unroll
;   for (int m = 0; m < 4; m++) {
;     const int rl = wr * 64 + m * 16 + fr; const float r = rsqrtf(rssg[rl] * (1.f / 1024.f) + 1e-6f);
; #pragma unroll
;     for (int i = 0; i < 2; i++) {
;       f32x4 g = acc[m][2 * i] * r, u = acc[m][2 * i + 1] * r, o;
	v_add_u32_e32 v0, 0, v85
	ds_read_b128 v[68:71], v0 offset:32768
	ds_read_b128 v[72:75], v0 offset:34816
	ds_read_b128 v[76:79], v0 offset:36864
	ds_read_b128 v[86:89], v0 offset:38912
	v_add_u32_e32 v0, 0, v84
	ds_read_b128 v[90:93], v0 offset:49152
	ds_read_b128 v[94:97], v0 offset:51200
	ds_read_b128 v[98:101], v0 offset:53248
	ds_read_b128 v[102:105], v0 offset:55296
	v_add_u32_e32 v0, 0, v83
	ds_read_b128 v[80:83], v0 offset:32768
	ds_read_b128 v[106:109], v0 offset:34816
	ds_read_b128 v[110:113], v0 offset:36864
	ds_read_b128 v[114:117], v0 offset:38912
	v_add_u32_e32 v0, 0, v2
	ds_read_b128 v[118:121], v0 offset:49152
	ds_read_b128 v[122:125], v0 offset:51200
	ds_read_b128 v[126:129], v0 offset:53248
	ds_read_b128 v[130:133], v0 offset:55296
	s_setprio 1
	s_waitcnt lgkmcnt(0)
	v_mfma_f32_16x16x32_bf16 v[64:67], v[90:93], v[68:71], v[64:67]
	v_mfma_f32_16x16x32_bf16 v[60:63], v[94:97], v[68:71], v[60:63]
	v_mfma_f32_16x16x32_bf16 v[56:59], v[98:101], v[68:71], v[56:59]
	v_mfma_f32_16x16x32_bf16 v[52:55], v[102:105], v[68:71], v[52:55]
	v_mfma_f32_16x16x32_bf16 v[48:51], v[90:93], v[72:75], v[48:51]
	v_mfma_f32_16x16x32_bf16 v[44:47], v[94:97], v[72:75], v[44:47]
	v_mfma_f32_16x16x32_bf16 v[68:71], v[98:101], v[72:75], v[40:43]
	v_mfma_f32_16x16x32_bf16 v[72:75], v[102:105], v[72:75], v[36:39]
	v_mfma_f32_16x16x32_bf16 v[32:35], v[90:93], v[76:79], v[32:35]
	v_mfma_f32_16x16x32_bf16 v[28:31], v[94:97], v[76:79], v[28:31]
	v_mfma_f32_16x16x32_bf16 v[134:137], v[98:101], v[76:79], v[24:27]
	v_mfma_f32_16x16x32_bf16 v[76:79], v[102:105], v[76:79], v[20:23]
	v_mfma_f32_16x16x32_bf16 v[16:19], v[90:93], v[86:89], v[16:19]
	v_mfma_f32_16x16x32_bf16 v[12:15], v[94:97], v[86:89], v[12:15]
	v_mfma_f32_16x16x32_bf16 v[90:93], v[98:101], v[86:89], v[8:11]
	v_mfma_f32_16x16x32_bf16 v[84:87], v[102:105], v[86:89], v[4:7]
	v_mfma_f32_16x16x32_bf16 v[64:67], v[118:121], v[80:83], v[64:67]
	v_mfma_f32_16x16x32_bf16 v[60:63], v[122:125], v[80:83], v[60:63]
	v_mfma_f32_16x16x32_bf16 v[56:59], v[126:129], v[80:83], v[56:59]
	v_mfma_f32_16x16x32_bf16 v[52:55], v[130:133], v[80:83], v[52:55]
	v_mfma_f32_16x16x32_bf16 v[40:43], v[118:121], v[106:109], v[48:51]
	v_mfma_f32_16x16x32_bf16 v[48:51], v[122:125], v[106:109], v[44:47]
	v_mfma_f32_16x16x32_bf16 v[36:39], v[126:129], v[106:109], v[68:71]
	v_mfma_f32_16x16x32_bf16 v[44:47], v[130:133], v[106:109], v[72:75]
	v_mfma_f32_16x16x32_bf16 v[24:27], v[118:121], v[110:113], v[32:35]
	v_mfma_f32_16x16x32_bf16 v[32:35], v[122:125], v[110:113], v[28:31]
	v_mfma_f32_16x16x32_bf16 v[20:23], v[126:129], v[110:113], v[134:137]
	v_mfma_f32_16x16x32_bf16 v[28:31], v[130:133], v[110:113], v[76:79]
	v_mfma_f32_16x16x32_bf16 v[8:11], v[118:121], v[114:117], v[16:19]
	v_mfma_f32_16x16x32_bf16 v[16:19], v[122:125], v[114:117], v[12:15]
	v_mfma_f32_16x16x32_bf16 v[4:7], v[126:129], v[114:117], v[90:93]
	v_mfma_f32_16x16x32_bf16 v[12:15], v[130:133], v[114:117], v[84:87]
	s_setprio 0
	v_mov_b32_e32 v2, v198
	s_mov_b32 s25, s89
	s_waitcnt vmcnt(0) lgkmcnt(0)
	s_add_u32 s34, s46, s25
	s_addc_u32 s35, s47, 0
	s_ashr_i32 s25, s24, 31
	v_and_b32_e32 v0, 15, v2
	s_lshl_b64 s[26:27], s[24:25], 2
	v_ashrrev_i32_e32 v1, 1, v2
	s_movk_i32 s4, 0xffc0
	s_add_u32 s26, s34, s26
	v_and_or_b32 v0, v1, s4, v0
	s_addc_u32 s27, s35, s27
	v_ashrrev_i32_e32 v1, 31, v0
	v_lshl_add_u64 v[68:69], v[0:1], 2, s[26:27]
	s_mov_b32 s26, 0xff9c000
	v_add_co_u32_e32 v70, vcc, s26, v68
	s_mov_b32 s25, s89
	s_nop 0
	v_addc_co_u32_e32 v71, vcc, 0, v69, vcc
	global_load_dword v74, v[70:71], off
	v_mov_b32_e32 v71, v64
	v_mov_b32_e32 v64, v61
	v_mov_b32_e32 v61, v66
	v_mov_b32_e32 v66, v63
	v_mov_b32_e32 v63, v56
	v_mov_b32_e32 v56, v53
	v_mov_b32_e32 v70, v60
	v_mov_b32_e32 v60, v62
	v_mov_b32_e32 v62, v52
	v_mov_b32_e32 v72, v54
	v_mov_b32_e32 v73, v58
	v_mov_b32_e32 v58, v55
	v_lshrrev_b32_e32 v1, 1, v2
	v_lshrrev_b32_e32 v2, 2, v2
	s_add_u32 s26, s46, s25
	v_and_b32_e32 v52, 12, v2
	v_add_u32_e32 v2, s24, v0
	s_addc_u32 s27, s47, 0
	s_mov_b64 s[24:25], 0xff9c000
	v_lshl_add_u64 v[54:55], v[68:69], 0, s[24:25]
	s_add_u32 s24, s26, 0x768000
	v_and_b32_e32 v1, 32, v1
	s_addc_u32 s25, s27, 0
	s_ashr_i32 s26, s31, 1
	v_or3_b32 v52, v1, s26, v52
	v_mov_b64_e32 v[0:1], s[24:25]
	v_mad_i64_i32 v[68:69], s[24:25], v2, s33, v[0:1]
	s_add_i32 s30, s30, s77
	s_add_i32 s29, s29, s2
	s_add_i32 s28, s28, s3
	s_cmpk_gt_i32 s30, 0x15ff
	s_waitcnt vmcnt(0)
; __device__ __forceinline__ unsigned pk2(float lo, float hi) { unsigned r; asm("v_cvt_pk_bf16_f32 %0, %1, %2" : "=v"(r) : "v"(lo), "v"(hi)); return r; }
; __device__ __forceinline__ float sigmoidf_(float x) { return __builtin_amdgcn_rcpf(1.0f + __expf(-x)); }
; __device__ __forceinline__ void gemm_GU(const Params& p, int item, char* lds) {
;     ...
; #pragma unroll
;   for (int m = 0; m < 4; m++) {
;     const int rl = wr * 64 + m * 16 + fr; const float r = rsqrtf(rssg[rl] * (1.f / 1024.f) + 1e-6f);
; #pragma unroll
;     for (int i = 0; i < 2; i++) {
;       f32x4 g = acc[m][2 * i] * r, u = acc[m][2 * i + 1] * r, o;
; #pragma unroll
;       for (int j = 0; j < 4; j++) o[j] = g[j] * sigmoidf_(g[j]) * u[j];
;       const int col = (n0 >> 1) + wc * 32 + i * 16 + fq * 4;
;       u32x2 w; w[0] = pk2(o[0], o[1]); w[1] = pk2(o[2], o[3]);
;       *(u32x2*)(U + (size_t)(m0 + rl) * DFF + col) = w;
;     }
	v_fmamk_f32 v53, v74, 0x3a800000, v200
	v_mul_f32_e32 v74, 0x4b800000, v53
	v_cmp_gt_f32_e32 vcc, s83, v53
	s_nop 1
	v_cndmask_b32_e32 v53, v53, v74, vcc
	v_rsq_f32_e32 v74, v53
	v_ashrrev_i32_e32 v53, 31, v52
	v_lshlrev_b64 v[52:53], 1, v[52:53]
	v_lshl_add_u64 v[68:69], v[68:69], 0, v[52:53]
	v_mul_f32_e32 v75, 0x45800000, v74
	v_cndmask_b32_e32 v74, v74, v75, vcc
	v_pk_mul_f32 v[60:61], v[60:61], v[74:75] op_sel_hi:[1,0]
	v_pk_mul_f32 v[70:71], v[70:71], v[74:75] op_sel_hi:[1,0]
	v_pk_mul_f32 v[64:65], v[64:65], v[74:75] op_sel_hi:[1,0]
	v_pk_mul_f32 v[66:67], v[66:67], v[74:75] op_sel_hi:[1,0]
	v_mul_f32_e32 v76, 0xbfb8aa3b, v61
	v_pk_mul_f32 v[62:63], v[62:63], v[74:75] op_sel_hi:[1,0]
	v_pk_mul_f32 v[56:57], v[56:57], v[74:75] op_sel_hi:[1,0]
	v_pk_mul_f32 v[72:73], v[72:73], v[74:75] op_sel_hi:[1,0]
	v_pk_mul_f32 v[58:59], v[58:59], v[74:75] op_sel_hi:[1,0]
	v_mul_f32_e32 v74, 0xbfb8aa3b, v71
	v_mul_f32_e32 v75, 0xbfb8aa3b, v65
	v_mul_f32_e32 v77, 0xbfb8aa3b, v67
	v_exp_f32_e32 v76, v76
	v_exp_f32_e32 v74, v74
	v_exp_f32_e32 v75, v75
	v_exp_f32_e32 v77, v77
	v_add_f32_e32 v76, 1.0, v76
	v_mul_f32_e32 v79, 0xbfb8aa3b, v57
	v_add_f32_e32 v74, 1.0, v74
	v_add_f32_e32 v75, 1.0, v75
	v_add_f32_e32 v77, 1.0, v77
	v_rcp_f32_e32 v76, v76
	v_mul_f32_e32 v80, 0xbfb8aa3b, v73
	v_exp_f32_e32 v79, v79
	v_rcp_f32_e32 v74, v74
	v_rcp_f32_e32 v75, v75
	v_rcp_f32_e32 v77, v77
	v_mul_f32_e32 v78, 0xbfb8aa3b, v63
	v_mul_f32_e32 v81, 0xbfb8aa3b, v59
	v_exp_f32_e32 v80, v80
	v_exp_f32_e32 v78, v78
	v_exp_f32_e32 v81, v81
	v_mul_f32_e32 v61, v61, v76
	v_add_f32_e32 v79, 1.0, v79
	v_mul_f32_e32 v71, v71, v74
	v_mul_f32_e32 v65, v65, v75
	v_mul_f32_e32 v67, v67, v77
	v_mul_f32_e32 v61, v60, v61
	v_add_f32_e32 v80, 1.0, v80
	v_rcp_f32_e32 v79, v79
	v_mul_f32_e32 v70, v70, v71
	v_mul_f32_e32 v64, v64, v65
	v_mul_f32_e32 v65, v66, v67
	v_cvt_pk_bf16_f32 v60, v70, v64
	v_cvt_pk_bf16_f32 v61, v61, v65
	v_add_f32_e32 v78, 1.0, v78
	global_store_dwordx2 v[68:69], v[60:61], off
	v_rcp_f32_e32 v60, v80
	v_add_f32_e32 v61, 1.0, v81
	v_rcp_f32_e32 v78, v78
	v_rcp_f32_e32 v61, v61
	v_mul_f32_e32 v57, v57, v79
	v_mul_f32_e32 v56, v56, v57
	v_mul_f32_e32 v57, v73, v60
	v_mul_f32_e32 v63, v63, v78
	v_mul_f32_e32 v57, v72, v57
	v_mul_f32_e32 v59, v59, v61
	v_mul_f32_e32 v62, v62, v63
	v_mul_f32_e32 v58, v58, v59
	v_cvt_pk_bf16_f32 v56, v62, v56
	v_cvt_pk_bf16_f32 v57, v57, v58
	global_store_dwordx2 v[68:69], v[56:57], off offset:32
	global_load_dword v58, v[54:55], off offset:64
	v_mov_b32_e32 v57, v40
	v_mov_b32_e32 v40, v49
	v_mov_b32_e32 v49, v42
	v_mov_b32_e32 v42, v51
	v_mov_b32_e32 v51, v36
	v_mov_b32_e32 v36, v45
	v_mov_b32_e32 v45, v38
	v_mov_b32_e32 v38, v47
	v_mov_b32_e32 v56, v48
	v_mov_b32_e32 v48, v50
	v_mov_b32_e32 v50, v44
	v_mov_b32_e32 v44, v46
	v_add_u32_e32 v46, 16, v2
	s_waitcnt vmcnt(0)
	v_fmamk_f32 v47, v58, 0x3a800000, v200
	v_mul_f32_e32 v58, 0x4b800000, v47
	v_cmp_gt_f32_e32 vcc, s83, v47
	s_nop 1
	v_cndmask_b32_e32 v47, v47, v58, vcc
	v_rsq_f32_e32 v58, v47
	v_mad_i64_i32 v[46:47], s[24:25], v46, s33, v[0:1]
	v_lshl_add_u64 v[46:47], v[46:47], 0, v[52:53]
	v_mul_f32_e32 v59, 0x45800000, v58
	v_cndmask_b32_e32 v58, v58, v59, vcc
	v_pk_mul_f32 v[56:57], v[56:57], v[58:59] op_sel_hi:[1,0]
	v_pk_mul_f32 v[40:41], v[40:41], v[58:59] op_sel_hi:[1,0]
	v_pk_mul_f32 v[48:49], v[48:49], v[58:59] op_sel_hi:[1,0]
	v_pk_mul_f32 v[42:43], v[42:43], v[58:59] op_sel_hi:[1,0]
	v_pk_mul_f32 v[36:37], v[36:37], v[58:59] op_sel_hi:[1,0]
	v_pk_mul_f32 v[38:39], v[38:39], v[58:59] op_sel_hi:[1,0]
	v_pk_mul_f32 v[50:51], v[50:51], v[58:59] op_sel_hi:[1,0]
	v_pk_mul_f32 v[44:45], v[44:45], v[58:59] op_sel_hi:[1,0]
	v_mul_f32_e32 v58, 0xbfb8aa3b, v57
	v_mul_f32_e32 v59, 0xbfb8aa3b, v41
	v_mul_f32_e32 v60, 0xbfb8aa3b, v49
	v_mul_f32_e32 v61, 0xbfb8aa3b, v43
	v_mul_f32_e32 v63, 0xbfb8aa3b, v37
	v_mul_f32_e32 v65, 0xbfb8aa3b, v39
	v_mul_f32_e32 v62, 0xbfb8aa3b, v51
	v_mul_f32_e32 v64, 0xbfb8aa3b, v45
	v_exp_f32_e32 v58, v58
	v_exp_f32_e32 v59, v59
	v_exp_f32_e32 v60, v60
	v_exp_f32_e32 v61, v61
	v_exp_f32_e32 v63, v63
	v_exp_f32_e32 v65, v65
	v_exp_f32_e32 v62, v62
	v_exp_f32_e32 v64, v64
	v_add_f32_e32 v58, 1.0, v58
	v_add_f32_e32 v59, 1.0, v59
	v_add_f32_e32 v60, 1.0, v60
	v_add_f32_e32 v61, 1.0, v61
	v_add_f32_e32 v63, 1.0, v63
	v_add_f32_e32 v65, 1.0, v65
	v_add_f32_e32 v62, 1.0, v62
	v_add_f32_e32 v64, 1.0, v64
	v_rcp_f32_e32 v58, v58
	v_rcp_f32_e32 v59, v59
	v_rcp_f32_e32 v60, v60
	v_rcp_f32_e32 v61, v61
	v_rcp_f32_e32 v63, v63
	v_rcp_f32_e32 v65, v65
	v_rcp_f32_e32 v62, v62
	v_rcp_f32_e32 v64, v64
	v_mul_f32_e32 v57, v57, v58
	v_mul_f32_e32 v41, v41, v59
	v_mul_f32_e32 v49, v49, v60
	v_mul_f32_e32 v43, v43, v61
	v_mul_f32_e32 v37, v37, v63
	v_mul_f32_e32 v39, v39, v65
	v_mul_f32_e32 v51, v51, v62
	v_mul_f32_e32 v45, v45, v64
	v_mul_f32_e32 v56, v56, v57
	v_mul_f32_e32 v40, v40, v41
	v_mul_f32_e32 v41, v48, v49
	v_mul_f32_e32 v42, v42, v43
	v_mul_f32_e32 v48, v36, v37
	v_mul_f32_e32 v39, v38, v39
	v_cvt_pk_bf16_f32 v36, v56, v40
	v_cvt_pk_bf16_f32 v37, v41, v42
	v_mul_f32_e32 v43, v50, v51
	v_mul_f32_e32 v44, v44, v45
	v_cvt_pk_bf16_f32 v38, v43, v48
	v_cvt_pk_bf16_f32 v39, v44, v39
	global_store_dwordx2 v[46:47], v[36:37], off
	global_store_dwordx2 v[46:47], v[38:39], off offset:32
	global_load_dword v38, v[54:55], off offset:128
	v_mov_b32_e32 v37, v24
	v_mov_b32_e32 v24, v33
	v_mov_b32_e32 v33, v26
	v_mov_b32_e32 v26, v35
	v_mov_b32_e32 v35, v20
	v_mov_b32_e32 v20, v29
	v_mov_b32_e32 v29, v22
	v_mov_b32_e32 v22, v31
	v_mov_b32_e32 v36, v32
	v_mov_b32_e32 v32, v34
	v_mov_b32_e32 v34, v28
	v_mov_b32_e32 v28, v30
	v_add_u32_e32 v30, 32, v2
	v_add_u32_e32 v2, 48, v2
	s_waitcnt vmcnt(0)
; __device__ __forceinline__ unsigned pk2(float lo, float hi) { unsigned r; asm("v_cvt_pk_bf16_f32 %0, %1, %2" : "=v"(r) : "v"(lo), "v"(hi)); return r; }
; __device__ __forceinline__ float sigmoidf_(float x) { return __builtin_amdgcn_rcpf(1.0f + __expf(-x)); }
; __device__ __forceinline__ void gemm_GU(const Params& p, int item, char* lds) {
;     ...
; #pragma unroll
;   for (int m = 0; m < 4; m++) {
;     const int rl = wr * 64 + m * 16 + fr; const float r = rsqrtf(rssg[rl] * (1.f / 1024.f) + 1e-6f);
; #pragma unroll
;     for (int i = 0; i < 2; i++) {
;       f32x4 g = acc[m][2 * i] * r, u = acc[m][2 * i + 1] * r, o;
; #pragma unroll
;       for (int j = 0; j < 4; j++) o[j] = g[j] * sigmoidf_(g[j]) * u[j];
;       const int col = (n0 >> 1) + wc * 32 + i * 16 + fq * 4;
;       u32x2 w; w[0] = pk2(o[0], o[1]); w[1] = pk2(o[2], o[3]);
;       *(u32x2*)(U + (size_t)(m0 + rl) * DFF + col) = w;
;     }
;   }
;   __syncthreads();
; __device__ __forceinline__ void run_phase(const Params& p, int ph, char* lds, int mode) {
;     ...
;     case 5: for (int it = B; it < 128 * 44; it += G) { if (mode == 1) gemm_GU_probe(p, it, lds); else if (EN(50)) gemm_GU(p, it, lds); } break;
	v_fmamk_f32 v31, v38, 0x3a800000, v200
	v_mul_f32_e32 v38, 0x4b800000, v31
	v_cmp_gt_f32_e32 vcc, s83, v31
	s_nop 1
	v_cndmask_b32_e32 v31, v31, v38, vcc
	v_rsq_f32_e32 v38, v31
	v_mad_i64_i32 v[30:31], s[24:25], v30, s33, v[0:1]
	v_lshl_add_u64 v[30:31], v[30:31], 0, v[52:53]
	v_mul_f32_e32 v39, 0x45800000, v38
	v_cndmask_b32_e32 v38, v38, v39, vcc
	v_pk_mul_f32 v[36:37], v[36:37], v[38:39] op_sel_hi:[1,0]
	v_pk_mul_f32 v[24:25], v[24:25], v[38:39] op_sel_hi:[1,0]
	v_pk_mul_f32 v[32:33], v[32:33], v[38:39] op_sel_hi:[1,0]
	v_pk_mul_f32 v[26:27], v[26:27], v[38:39] op_sel_hi:[1,0]
	v_pk_mul_f32 v[20:21], v[20:21], v[38:39] op_sel_hi:[1,0]
	v_pk_mul_f32 v[22:23], v[22:23], v[38:39] op_sel_hi:[1,0]
	v_pk_mul_f32 v[34:35], v[34:35], v[38:39] op_sel_hi:[1,0]
	v_pk_mul_f32 v[28:29], v[28:29], v[38:39] op_sel_hi:[1,0]
	v_mul_f32_e32 v38, 0xbfb8aa3b, v37
	v_mul_f32_e32 v39, 0xbfb8aa3b, v25
	v_mul_f32_e32 v40, 0xbfb8aa3b, v33
	v_mul_f32_e32 v41, 0xbfb8aa3b, v27
	v_mul_f32_e32 v43, 0xbfb8aa3b, v21
	v_mul_f32_e32 v45, 0xbfb8aa3b, v23
	v_mul_f32_e32 v42, 0xbfb8aa3b, v35
	v_mul_f32_e32 v44, 0xbfb8aa3b, v29
	v_exp_f32_e32 v38, v38
	v_exp_f32_e32 v39, v39
	v_exp_f32_e32 v40, v40
	v_exp_f32_e32 v41, v41
	v_exp_f32_e32 v43, v43
	v_exp_f32_e32 v45, v45
	v_exp_f32_e32 v42, v42
	v_exp_f32_e32 v44, v44
	v_add_f32_e32 v38, 1.0, v38
	v_add_f32_e32 v39, 1.0, v39
	v_add_f32_e32 v40, 1.0, v40
	v_add_f32_e32 v41, 1.0, v41
	v_add_f32_e32 v43, 1.0, v43
	v_add_f32_e32 v45, 1.0, v45
	v_add_f32_e32 v42, 1.0, v42
	v_add_f32_e32 v44, 1.0, v44
	v_rcp_f32_e32 v38, v38
	v_rcp_f32_e32 v39, v39
	v_rcp_f32_e32 v40, v40
	v_rcp_f32_e32 v41, v41
	v_rcp_f32_e32 v43, v43
	v_rcp_f32_e32 v45, v45
	v_rcp_f32_e32 v42, v42
	v_rcp_f32_e32 v44, v44
	v_mul_f32_e32 v37, v37, v38
	v_mul_f32_e32 v25, v25, v39
	v_mul_f32_e32 v33, v33, v40
	v_mul_f32_e32 v27, v27, v41
	v_mul_f32_e32 v21, v21, v43
	v_mul_f32_e32 v23, v23, v45
	v_mul_f32_e32 v35, v35, v42
	v_mul_f32_e32 v29, v29, v44
	v_mul_f32_e32 v36, v36, v37
	v_mul_f32_e32 v24, v24, v25
	v_mul_f32_e32 v25, v32, v33
	v_mul_f32_e32 v26, v26, v27
	v_mul_f32_e32 v32, v20, v21
	v_mul_f32_e32 v23, v22, v23
	v_cvt_pk_bf16_f32 v20, v36, v24
	v_cvt_pk_bf16_f32 v21, v25, v26
	v_mul_f32_e32 v27, v34, v35
	v_mul_f32_e32 v28, v28, v29
	v_cvt_pk_bf16_f32 v22, v27, v32
	v_cvt_pk_bf16_f32 v23, v28, v23
	global_store_dwordx2 v[30:31], v[20:21], off
	global_store_dwordx2 v[30:31], v[22:23], off offset:32
	global_load_dword v22, v[54:55], off offset:192
	v_mov_b32_e32 v20, v16
	v_mov_b32_e32 v16, v18
	v_mov_b32_e32 v18, v12
	v_mov_b32_e32 v12, v14
	v_mov_b32_e32 v21, v8
	v_mov_b32_e32 v8, v17
	v_mov_b32_e32 v17, v10
	v_mov_b32_e32 v10, v19
	v_mov_b32_e32 v19, v4
	v_mov_b32_e32 v4, v13
	v_mov_b32_e32 v13, v6
	v_mov_b32_e32 v6, v15
	v_mad_i64_i32 v[0:1], s[24:25], v2, s33, v[0:1]
	v_lshl_add_u64 v[0:1], v[0:1], 0, v[52:53]
	s_waitcnt vmcnt(0)
	v_fmamk_f32 v14, v22, 0x3a800000, v200
	v_mul_f32_e32 v15, 0x4b800000, v14
	v_cmp_gt_f32_e32 vcc, s83, v14
	s_nop 1
	v_cndmask_b32_e32 v14, v14, v15, vcc
	v_rsq_f32_e32 v14, v14
	s_nop 0
	v_mul_f32_e32 v2, 0x45800000, v14
	v_cndmask_b32_e32 v2, v14, v2, vcc
	v_pk_mul_f32 v[14:15], v[20:21], v[2:3] op_sel_hi:[1,0]
	v_pk_mul_f32 v[8:9], v[8:9], v[2:3] op_sel_hi:[1,0]
	v_pk_mul_f32 v[16:17], v[16:17], v[2:3] op_sel_hi:[1,0]
	v_pk_mul_f32 v[10:11], v[10:11], v[2:3] op_sel_hi:[1,0]
	v_pk_mul_f32 v[4:5], v[4:5], v[2:3] op_sel_hi:[1,0]
	v_pk_mul_f32 v[6:7], v[6:7], v[2:3] op_sel_hi:[1,0]
	v_pk_mul_f32 v[18:19], v[18:19], v[2:3] op_sel_hi:[1,0]
	v_pk_mul_f32 v[12:13], v[12:13], v[2:3] op_sel_hi:[1,0]
	v_mul_f32_e32 v2, 0xbfb8aa3b, v15
	v_mul_f32_e32 v20, 0xbfb8aa3b, v9
	v_mul_f32_e32 v21, 0xbfb8aa3b, v17
	v_mul_f32_e32 v22, 0xbfb8aa3b, v11
	v_mul_f32_e32 v24, 0xbfb8aa3b, v5
	v_mul_f32_e32 v26, 0xbfb8aa3b, v7
	v_mul_f32_e32 v23, 0xbfb8aa3b, v19
	v_mul_f32_e32 v25, 0xbfb8aa3b, v13
	v_exp_f32_e32 v2, v2
	v_exp_f32_e32 v20, v20
	v_exp_f32_e32 v21, v21
	v_exp_f32_e32 v22, v22
	v_exp_f32_e32 v24, v24
	v_exp_f32_e32 v26, v26
	v_exp_f32_e32 v23, v23
	v_exp_f32_e32 v25, v25
	v_add_f32_e32 v2, 1.0, v2
	v_add_f32_e32 v20, 1.0, v20
	v_add_f32_e32 v21, 1.0, v21
	v_add_f32_e32 v22, 1.0, v22
	v_add_f32_e32 v24, 1.0, v24
	v_add_f32_e32 v26, 1.0, v26
	v_add_f32_e32 v23, 1.0, v23
	v_add_f32_e32 v25, 1.0, v25
	v_rcp_f32_e32 v2, v2
	v_rcp_f32_e32 v20, v20
	v_rcp_f32_e32 v21, v21
	v_rcp_f32_e32 v22, v22
	v_rcp_f32_e32 v24, v24
	v_rcp_f32_e32 v26, v26
	v_rcp_f32_e32 v23, v23
	v_rcp_f32_e32 v25, v25
	v_mul_f32_e32 v2, v15, v2
	v_mul_f32_e32 v9, v9, v20
	v_mul_f32_e32 v15, v17, v21
	v_mul_f32_e32 v11, v11, v22
	v_mul_f32_e32 v5, v5, v24
	v_mul_f32_e32 v7, v7, v26
	v_mul_f32_e32 v17, v19, v23
	v_mul_f32_e32 v13, v13, v25
	v_mul_f32_e32 v2, v14, v2
	v_mul_f32_e32 v8, v8, v9
	v_mul_f32_e32 v9, v16, v15
	v_mul_f32_e32 v10, v10, v11
	v_mul_f32_e32 v14, v4, v5
	v_mul_f32_e32 v7, v6, v7
	v_cvt_pk_bf16_f32 v4, v2, v8
	v_cvt_pk_bf16_f32 v5, v9, v10
	v_mul_f32_e32 v11, v18, v17
	v_mul_f32_e32 v12, v12, v13
	v_cvt_pk_bf16_f32 v6, v11, v14
	v_cvt_pk_bf16_f32 v7, v12, v7
	global_store_dwordx2 v[0:1], v[4:5], off
	global_store_dwordx2 v[0:1], v[6:7], off offset:32
	s_cbranch_scc0 .LBB0_108

; __device__ __forceinline__ unsigned char* WS(const Params& p) { unsigned z = 0; asm volatile("" : "+s"(z)); return p.ws + z; }
; __device__ __forceinline__ void run_phase(const Params& p, int ph, char* lds, int mode) {
;     ...
;       for (int it = B; it < 1024; it += G) { if (EN(40)) gemm_RES((const bf16_t*)(WS(p) + OFF_Y), 1024, wo, xin, p.out, (bf16_t*)(WS(p) + OFF_XB), (float*)(WS(p) + OFF_RSS) + T, it, lds); __syncthreads(); }
.LBB0_124:
	s_or_b64 exec, exec, s[34:35]
	s_add_i32 s42, s42, s77
	s_add_i32 s41, s41, s38
	s_add_i32 s40, s40, s39
	s_cmpk_gt_i32 s42, 0x3ff
	s_waitcnt lgkmcnt(0)
	s_cbranch_scc1 .LBB0_135

; __device__ __forceinline__ void gemm_mainloop_d(const bf16_t* __restrict__ Ap, int lda, const bf16_t* __restrict__ Bt, int K,
;                                                 int m0, int n0, f32x4 (&acc)[4][4], char* lds) {
;     ...
;   for (int kt = 0; kt < nk; kt++) {
;     const int st = kt & 1;
;     if (kt + 1 < nk) dma(kt + 1, st ^ 1);
;     const char* la = lds + st * 32768; const char* lb = la + 16384;
;     bf16x8 af[2][4], bfv[2][4];
; #pragma unroll
;     for (int kc = 0; kc < 2; kc++) {
; #pragma unroll
;       for (int m = 0; m < 4; m++) { const int row = wr * 64 + m * 16 + fr; af[kc][m] = *(const bf16x8*)(la + (row * 8 + ((kc * 4 + fq) ^ ((row >> 1) & 7))) * 16); }
; #pragma unroll
;       for (int n = 0; n < 4; n++) { const int row = wc * 64 + n * 16 + fr; bfv[kc][n] = *(const bf16x8*)(lb + (row * 8 + ((kc * 4 + fq) ^ ((row >> 1) & 7))) * 16); }
;     }
;     __builtin_amdgcn_s_setprio(1);
; #pragma unroll
;     for (int kc = 0; kc < 2; kc++)
; #pragma unroll
;       for (int m = 0; m < 4; m++)
; #pragma unroll
;         for (int n = 0; n < 4; n++) acc[m][n] = __builtin_amdgcn_mfma_f32_16x16x32_bf16(bfv[kc][n], af[kc][m], acc[m][n], 0, 0, 0);
;     __builtin_amdgcn_s_setprio(0);
;     asm volatile("s_waitcnt vmcnt(0) lgkmcnt(0)" ::: "memory"); __builtin_amdgcn_s_barrier(); asm volatile("" ::: "memory");
;   }
.LBB0_126:
	s_setprio 3
	s_and_b32 s37, s34, 0x8000
	s_xor_b32 s43, s37, 0x8000
	s_add_i32 s43, s43, vcc_hi
	s_mov_b32 m0, s43
	s_add_i32 vcc_lo, s43, 0x4000
	global_load_lds_dwordx4 v150, s[46:47]
	s_mov_b32 m0, vcc_lo
	s_add_i32 vcc_lo, s43, 0x1000
	global_load_lds_dwordx4 v151, s[46:47]
	s_mov_b32 m0, vcc_lo
	s_add_i32 vcc_lo, s43, 0x5000
	global_load_lds_dwordx4 v152, s[46:47]
	s_mov_b32 m0, vcc_lo
	s_add_i32 vcc_lo, s43, 0x2000
	global_load_lds_dwordx4 v153, s[46:47]
	s_mov_b32 m0, vcc_lo
	s_add_i32 vcc_lo, s43, 0x6000
	global_load_lds_dwordx4 v154, s[46:47]
	s_mov_b32 m0, vcc_lo
	s_add_i32 vcc_lo, s43, 0x3000
	global_load_lds_dwordx4 v155, s[46:47]
	s_mov_b32 m0, vcc_lo
	s_add_i32 vcc_lo, s43, 0x7000
	global_load_lds_dwordx4 v156, s[46:47]
	s_mov_b32 m0, vcc_lo
	s_nop 0
	global_load_lds_dwordx4 v157, s[46:47]
	v_add_u32_e32 v150, 0x80, v150
	v_add_u32_e32 v151, 0x80, v151
	v_add_u32_e32 v152, 0x80, v152
	v_add_u32_e32 v153, 0x80, v153
	v_add_u32_e32 v154, 0x80, v154
	v_add_u32_e32 v155, 0x80, v155
	v_add_u32_e32 v156, 0x80, v156
	v_add_u32_e32 v157, 0x80, v157
	v_add_u32_e32 v98, s37, v85
	v_add_u32_e32 v114, s37, v84
	v_add_u32_e32 v130, s37, v83
	v_add_u32_e32 v146, s37, v2
	ds_read_b128 v[86:89], v98
	ds_read_b128 v[90:93], v98 offset:2048
	ds_read_b128 v[94:97], v98 offset:4096
	ds_read_b128 v[98:101], v98 offset:6144
	ds_read_b128 v[102:105], v114 offset:16384
	ds_read_b128 v[106:109], v114 offset:18432
	ds_read_b128 v[110:113], v114 offset:20480
	ds_read_b128 v[114:117], v114 offset:22528
	ds_read_b128 v[118:121], v130
	ds_read_b128 v[122:125], v130 offset:2048
	ds_read_b128 v[126:129], v130 offset:4096
	ds_read_b128 v[130:133], v130 offset:6144
	ds_read_b128 v[134:137], v146 offset:16384
	ds_read_b128 v[138:141], v146 offset:18432
	ds_read_b128 v[142:145], v146 offset:20480
	ds_read_b128 v[146:149], v146 offset:22528
	s_setprio 1
	s_waitcnt lgkmcnt(0)
	v_mfma_f32_16x16x32_bf16 v[64:67], v[102:105], v[86:89], v[64:67]
	v_mfma_f32_16x16x32_bf16 v[60:63], v[106:109], v[86:89], v[60:63]
	v_mfma_f32_16x16x32_bf16 v[56:59], v[110:113], v[86:89], v[56:59]
	v_mfma_f32_16x16x32_bf16 v[52:55], v[114:117], v[86:89], v[52:55]
	v_mfma_f32_16x16x32_bf16 v[48:51], v[102:105], v[90:93], v[48:51]
	v_mfma_f32_16x16x32_bf16 v[44:47], v[106:109], v[90:93], v[44:47]
	v_mfma_f32_16x16x32_bf16 v[40:43], v[110:113], v[90:93], v[40:43]
	v_mfma_f32_16x16x32_bf16 v[36:39], v[114:117], v[90:93], v[36:39]
	v_mfma_f32_16x16x32_bf16 v[32:35], v[102:105], v[94:97], v[32:35]
	v_mfma_f32_16x16x32_bf16 v[28:31], v[106:109], v[94:97], v[28:31]
	v_mfma_f32_16x16x32_bf16 v[24:27], v[110:113], v[94:97], v[24:27]
	v_mfma_f32_16x16x32_bf16 v[20:23], v[114:117], v[94:97], v[20:23]
	v_mfma_f32_16x16x32_bf16 v[16:19], v[102:105], v[98:101], v[16:19]
	v_mfma_f32_16x16x32_bf16 v[12:15], v[106:109], v[98:101], v[12:15]
	v_mfma_f32_16x16x32_bf16 v[8:11], v[110:113], v[98:101], v[8:11]
	v_mfma_f32_16x16x32_bf16 v[4:7], v[114:117], v[98:101], v[4:7]
	v_mfma_f32_16x16x32_bf16 v[64:67], v[134:137], v[118:121], v[64:67]
	v_mfma_f32_16x16x32_bf16 v[60:63], v[138:141], v[118:121], v[60:63]
	v_mfma_f32_16x16x32_bf16 v[56:59], v[142:145], v[118:121], v[56:59]
	v_mfma_f32_16x16x32_bf16 v[52:55], v[146:149], v[118:121], v[52:55]
	v_mfma_f32_16x16x32_bf16 v[48:51], v[134:137], v[122:125], v[48:51]
	v_mfma_f32_16x16x32_bf16 v[44:47], v[138:141], v[122:125], v[44:47]
	v_mfma_f32_16x16x32_bf16 v[40:43], v[142:145], v[122:125], v[40:43]
	v_mfma_f32_16x16x32_bf16 v[36:39], v[146:149], v[122:125], v[36:39]
	v_mfma_f32_16x16x32_bf16 v[32:35], v[134:137], v[126:129], v[32:35]
	v_mfma_f32_16x16x32_bf16 v[28:31], v[138:141], v[126:129], v[28:31]
	v_mfma_f32_16x16x32_bf16 v[24:27], v[142:145], v[126:129], v[24:27]
	v_mfma_f32_16x16x32_bf16 v[20:23], v[146:149], v[126:129], v[20:23]
	v_mfma_f32_16x16x32_bf16 v[16:19], v[134:137], v[130:133], v[16:19]
	v_mfma_f32_16x16x32_bf16 v[12:15], v[138:141], v[130:133], v[12:15]
	v_mfma_f32_16x16x32_bf16 v[8:11], v[142:145], v[130:133], v[8:11]
	v_mfma_f32_16x16x32_bf16 v[4:7], v[146:149], v[130:133], v[4:7]
	s_setprio 0
	s_waitcnt vmcnt(0) lgkmcnt(0)
	s_barrier
	s_add_u32 s30, s30, 0x80
	s_addc_u32 s31, s31, 0
	s_add_i32 s34, s34, 0x8000
	s_cmpk_eq_i32 s30, 0x780
	s_cbranch_scc0 .LBB0_126
; __device__ __forceinline__ void gemm_mainloop_d(const bf16_t* __restrict__ Ap, int lda, const bf16_t* __restrict__ Bt, int K,
;                                                 int m0, int n0, f32x4 (&acc)[4][4], char* lds) {
;     ...
; #pragma unroll
;     for (int kc = 0; kc < 2; kc++)
; #pragma unroll
;       for (int m = 0; m < 4; m++)
; #pragma unroll
;         for (int n = 0; n < 4; n++) acc[m][n] = __builtin_amdgcn_mfma_f32_16x16x32_bf16(bfv[kc][n], af[kc][m], acc[m][n], 0, 0, 0);
;     __builtin_amdgcn_s_setprio(0);
;     asm volatile("s_waitcnt vmcnt(0) lgkmcnt(0)" ::: "memory"); __builtin_amdgcn_s_barrier(); asm volatile("" ::: "memory");
	v_add_u32_e32 v0, 0, v85
	ds_read_b128 v[68:71], v0 offset:32768
	ds_read_b128 v[72:75], v0 offset:34816
	ds_read_b128 v[76:79], v0 offset:36864
	ds_read_b128 v[86:89], v0 offset:38912
	v_add_u32_e32 v0, 0, v84
	ds_read_b128 v[90:93], v0 offset:49152
	ds_read_b128 v[94:97], v0 offset:51200
	ds_read_b128 v[98:101], v0 offset:53248
	ds_read_b128 v[102:105], v0 offset:55296
	v_add_u32_e32 v0, 0, v83
	s_add_u32 s30, s46, s35
	ds_read_b128 v[80:83], v0 offset:32768
	ds_read_b128 v[106:109], v0 offset:34816
	ds_read_b128 v[110:113], v0 offset:36864
	ds_read_b128 v[114:117], v0 offset:38912
	v_add_u32_e32 v0, 0, v2
	s_addc_u32 s31, s47, 0
	ds_read_b128 v[118:121], v0 offset:49152
	ds_read_b128 v[122:125], v0 offset:51200
	ds_read_b128 v[126:129], v0 offset:53248
	ds_read_b128 v[130:133], v0 offset:55296
	s_add_u32 s36, s46, s36
	s_addc_u32 s37, s47, 0
	s_add_u32 s34, s30, 0x65a8000
	s_addc_u32 s35, s31, 0
	s_add_u32 s30, s36, 0xff9c000
	s_addc_u32 s31, s37, 0
	s_setprio 1
	s_waitcnt lgkmcnt(0)
	v_mfma_f32_16x16x32_bf16 v[56:59], v[98:101], v[68:71], v[56:59]
	v_mfma_f32_16x16x32_bf16 v[48:51], v[90:93], v[72:75], v[48:51]
	v_mfma_f32_16x16x32_bf16 v[44:47], v[94:97], v[72:75], v[44:47]
	v_mfma_f32_16x16x32_bf16 v[40:43], v[98:101], v[72:75], v[40:43]
	v_mfma_f32_16x16x32_bf16 v[36:39], v[102:105], v[72:75], v[36:39]
	v_mfma_f32_16x16x32_bf16 v[32:35], v[90:93], v[76:79], v[32:35]
	v_mfma_f32_16x16x32_bf16 v[28:31], v[94:97], v[76:79], v[28:31]
	v_mfma_f32_16x16x32_bf16 v[24:27], v[98:101], v[76:79], v[24:27]
	v_mfma_f32_16x16x32_bf16 v[20:23], v[102:105], v[76:79], v[20:23]
	v_mfma_f32_16x16x32_bf16 v[16:19], v[90:93], v[86:89], v[16:19]
	v_mfma_f32_16x16x32_bf16 v[12:15], v[94:97], v[86:89], v[12:15]
	v_mfma_f32_16x16x32_bf16 v[8:11], v[98:101], v[86:89], v[8:11]
	v_mfma_f32_16x16x32_bf16 v[4:7], v[102:105], v[86:89], v[4:7]
	v_mfma_f32_16x16x32_bf16 v[64:67], v[90:93], v[68:71], v[64:67]
	v_mfma_f32_16x16x32_bf16 v[60:63], v[94:97], v[68:71], v[60:63]
	v_mfma_f32_16x16x32_bf16 v[52:55], v[102:105], v[68:71], v[52:55]
	v_mfma_f32_16x16x32_bf16 v[56:59], v[126:129], v[80:83], v[56:59]
	v_mfma_f32_16x16x32_bf16 v[48:51], v[118:121], v[106:109], v[48:51]
	v_mfma_f32_16x16x32_bf16 v[44:47], v[122:125], v[106:109], v[44:47]
	v_mfma_f32_16x16x32_bf16 v[40:43], v[126:129], v[106:109], v[40:43]
	v_mfma_f32_16x16x32_bf16 v[36:39], v[130:133], v[106:109], v[36:39]
	v_mfma_f32_16x16x32_bf16 v[32:35], v[118:121], v[110:113], v[32:35]
	v_mfma_f32_16x16x32_bf16 v[28:31], v[122:125], v[110:113], v[28:31]
	v_mfma_f32_16x16x32_bf16 v[24:27], v[126:129], v[110:113], v[24:27]
	v_mfma_f32_16x16x32_bf16 v[20:23], v[130:133], v[110:113], v[20:23]
	v_mfma_f32_16x16x32_bf16 v[16:19], v[118:121], v[114:117], v[16:19]
	v_mfma_f32_16x16x32_bf16 v[12:15], v[122:125], v[114:117], v[12:15]
	v_mfma_f32_16x16x32_bf16 v[8:11], v[126:129], v[114:117], v[8:11]
	v_mfma_f32_16x16x32_bf16 v[4:7], v[130:133], v[114:117], v[4:7]
	v_mfma_f32_16x16x32_bf16 v[64:67], v[118:121], v[80:83], v[64:67]
	v_mfma_f32_16x16x32_bf16 v[60:63], v[122:125], v[80:83], v[60:63]
	v_mfma_f32_16x16x32_bf16 v[68:71], v[130:133], v[80:83], v[52:55]
	s_setprio 0
	v_mov_b32_e32 v0, v198
	s_waitcnt vmcnt(0) lgkmcnt(0)
; __device__ __forceinline__ unsigned pk2(float lo, float hi) { unsigned r; asm("v_cvt_pk_bf16_f32 %0, %1, %2" : "=v"(r) : "v"(lo), "v"(hi)); return r; }
; __device__ __forceinline__ float bflo(unsigned u) { return __uint_as_float(u << 16); }
; __device__ __forceinline__ float bfhi(unsigned u) { return __uint_as_float(u & 0xffff0000u); }
; __device__ __forceinline__ void gemm_RES(const bf16_t* A, int K, const bf16_t* Bt, const float* xin, float* xout, bf16_t* xb, float* rss, int item, char* lds) {
;     ...
; #pragma unroll
;   for (int m = 0; m < 4; m++) {
;     const int rowg = m0 + wr * 64 + m * 16 + fr;
;     const size_t ro = (size_t)rowg * DM;
;     float sq = 0.f;
; #pragma unroll
;     for (int n = 0; n < 4; n++) {
;       const int col = n0 + wc * 64 + n * 16 + fq * 4;
;       f32x4 xv = *(const f32x4*)(xin + ro + col);
;       const f32x4 xn = xv + acc[m][n];
;       *(f32x4*)(xout + ro + col) = xn;
;       u32x2 w; w[0] = pk2(xn[0], xn[1]); w[1] = pk2(xn[2], xn[3]); *(u32x2*)(xb + ro + col) = w;
;       const float b0 = bflo(w[0]), b1 = bfhi(w[0]), b2 = bflo(w[1]), b3 = bfhi(w[1]);
;       sq += b0 * b0 + b1 * b1 + b2 * b2 + b3 * b3;
;     }
;     sq += __shfl_xor(sq, 16); sq += __shfl_xor(sq, 32);
;     if (fq == 0) unsafeAtomicAdd(rss + rowg, sq);
;   }
	v_readlane_b32 s4, v252, 35
	v_ashrrev_i32_e32 v2, 1, v0
	v_and_b32_e32 v2, 0xffffffc0, v2
	v_add_u32_e32 v2, s3, v2
	v_bfe_u32 v82, v0, 4, 2
	v_and_or_b32 v52, v0, 15, v2
	v_and_b32_e32 v1, 64, v0
	v_lshlrev_b32_e32 v0, 2, v82
	v_ashrrev_i32_e32 v53, 31, v52
	v_or3_b32 v78, v0, v1, s2
	v_lshlrev_b64 v[54:55], 12, v[52:53]
	v_lshl_add_u64 v[0:1], s[26:27], 0, v[54:55]
	v_lshlrev_b32_e32 v2, 2, v78
	v_lshl_add_u64 v[76:77], v[0:1], 0, v[2:3]
	global_load_dwordx4 v[72:75], v[76:77], off
	v_lshlrev_b32_e32 v0, 1, v78
	v_lshlrev_b64 v[78:79], 11, v[52:53]
	v_readlane_b32 s18, v252, 49
	v_readlane_b32 s19, v252, 50
	v_mov_b32_e32 v1, v3
	v_lshl_add_u64 v[78:79], s[34:35], 0, v[78:79]
	v_lshl_add_u64 v[54:55], s[18:19], 0, v[54:55]
	v_lshl_add_u64 v[80:81], v[54:55], 0, v[2:3]
	v_lshl_add_u64 v[78:79], v[78:79], 0, v[0:1]
	v_readlane_b32 s5, v252, 36
	v_readlane_b32 s6, v252, 37
	v_readlane_b32 s7, v252, 38
	v_readlane_b32 s8, v252, 39
	v_readlane_b32 s9, v252, 40
	v_readlane_b32 s10, v252, 41
	v_readlane_b32 s11, v252, 42
	v_readlane_b32 s12, v252, 43
	v_readlane_b32 s13, v252, 44
	v_readlane_b32 s14, v252, 45
	v_readlane_b32 s15, v252, 46
	v_readlane_b32 s16, v252, 47
	v_readlane_b32 s17, v252, 48
	s_waitcnt vmcnt(0)
	v_pk_add_f32 v[66:67], v[66:67], v[74:75]
	v_pk_add_f32 v[64:65], v[64:65], v[72:73]
	global_store_dwordx4 v[80:81], v[64:67], off
	v_cvt_pk_bf16_f32 v54, v64, v65
	v_cvt_pk_bf16_f32 v55, v66, v67
	global_store_dwordx2 v[78:79], v[54:55], off
	global_load_dwordx4 v[64:67], v[76:77], off offset:64
	s_waitcnt vmcnt(0)
	v_pk_add_f32 v[62:63], v[62:63], v[66:67]
	v_pk_add_f32 v[60:61], v[60:61], v[64:65]
	global_store_dwordx4 v[80:81], v[60:63], off offset:64
	v_cvt_pk_bf16_f32 v64, v60, v61
	v_cvt_pk_bf16_f32 v65, v62, v63
	global_store_dwordx2 v[78:79], v[64:65], off offset:32
	global_load_dwordx4 v[60:63], v[76:77], off offset:128
	v_lshlrev_b32_e32 v66, 16, v54
	v_and_b32_e32 v54, 0xffff0000, v54
	v_mul_f32_e32 v54, v54, v54
	v_lshlrev_b32_e32 v67, 16, v55
	v_fmac_f32_e32 v54, v66, v66
	v_and_b32_e32 v55, 0xffff0000, v55
	v_fmac_f32_e32 v54, v67, v67
	v_fmac_f32_e32 v54, v55, v55
	v_lshlrev_b32_e32 v55, 16, v64
	v_and_b32_e32 v64, 0xffff0000, v64
	v_mul_f32_e32 v64, v64, v64
	v_lshlrev_b32_e32 v66, 16, v65
	v_fmac_f32_e32 v64, v55, v55
	v_and_b32_e32 v65, 0xffff0000, v65
	v_fmac_f32_e32 v64, v66, v66
	v_fmac_f32_e32 v64, v65, v65
	v_add_f32_e32 v54, v54, v64
	s_waitcnt vmcnt(0)
	v_pk_add_f32 v[58:59], v[58:59], v[62:63]
	v_pk_add_f32 v[56:57], v[56:57], v[60:61]
	global_store_dwordx4 v[80:81], v[56:59], off offset:128
	v_cvt_pk_bf16_f32 v62, v56, v57
	v_cvt_pk_bf16_f32 v63, v58, v59
	global_store_dwordx2 v[78:79], v[62:63], off offset:64
	global_load_dwordx4 v[58:61], v[76:77], off offset:192
	v_lshlrev_b32_e32 v55, 16, v62
	v_and_b32_e32 v62, 0xffff0000, v62
	v_mul_f32_e32 v62, v62, v62
	v_lshlrev_b32_e32 v64, 16, v63
	v_fmac_f32_e32 v62, v55, v55
	v_and_b32_e32 v63, 0xffff0000, v63
	v_fmac_f32_e32 v62, v64, v64
	v_fmac_f32_e32 v62, v63, v63
	v_add_f32_e32 v54, v54, v62
	v_and_b32_e32 v57, 64, v218
	v_xor_b32_e32 v56, 16, v218
	v_add_u32_e32 v57, 64, v57
	v_cmp_lt_i32_e32 vcc, v56, v57
	s_waitcnt vmcnt(0)
	v_pk_add_f32 v[58:59], v[68:69], v[58:59]
	s_nop 0
	v_cvt_pk_bf16_f32 v62, v58, v59
	v_pk_add_f32 v[60:61], v[70:71], v[60:61]
	v_and_b32_e32 v64, 0xffff0000, v62
	v_lshlrev_b32_e32 v55, 16, v62
	v_mul_f32_e32 v64, v64, v64
	v_cvt_pk_bf16_f32 v63, v60, v61
	v_fmac_f32_e32 v64, v55, v55
	v_lshlrev_b32_e32 v65, 16, v63
	v_and_b32_e32 v66, 0xffff0000, v63
	v_fmac_f32_e32 v64, v65, v65
	v_cndmask_b32_e32 v56, v218, v56, vcc
	v_fmac_f32_e32 v64, v66, v66
	v_lshlrev_b32_e32 v56, 2, v56
	v_add_f32_e32 v54, v54, v64
	ds_bpermute_b32 v55, v56, v54
	v_xor_b32_e32 v64, 32, v218
	v_cmp_lt_i32_e32 vcc, v64, v57
	global_store_dwordx4 v[80:81], v[58:61], off offset:192
	global_store_dwordx2 v[78:79], v[62:63], off offset:96
	v_cndmask_b32_e32 v57, v218, v64, vcc
	s_waitcnt lgkmcnt(0)
	v_add_f32_e32 v54, v54, v55
	v_lshlrev_b32_e32 v57, 2, v57
	ds_bpermute_b32 v55, v57, v54
	v_cmp_eq_u32_e32 vcc, 0, v82
	s_and_saveexec_b64 s[36:37], vcc
	s_cbranch_execz .LBB0_129
	v_lshl_add_u64 v[58:59], v[52:53], 2, s[30:31]
	s_waitcnt lgkmcnt(0)
	v_add_f32_e32 v53, v54, v55
	global_atomic_add_f32 v[58:59], v53, off

; __device__ __forceinline__ void gemm_mainloop_d(const bf16_t* __restrict__ Ap, int lda, const bf16_t* __restrict__ Bt, int K,
;                                                 int m0, int n0, f32x4 (&acc)[4][4], char* lds) {
;     ...
;   for (int kt = 0; kt < nk; kt++) {
;     const int st = kt & 1;
;     if (kt + 1 < nk) dma(kt + 1, st ^ 1);
;     const char* la = lds + st * 32768; const char* lb = la + 16384;
;     bf16x8 af[2][4], bfv[2][4];
; #pragma unroll
;     for (int kc = 0; kc < 2; kc++) {
; #pragma unroll
;       for (int m = 0; m < 4; m++) { const int row = wr * 64 + m * 16 + fr; af[kc][m] = *(const bf16x8*)(la + (row * 8 + ((kc * 4 + fq) ^ ((row >> 1) & 7))) * 16); }
; #pragma unroll
;       for (int n = 0; n < 4; n++) { const int row = wc * 64 + n * 16 + fr; bfv[kc][n] = *(const bf16x8*)(lb + (row * 8 + ((kc * 4 + fq) ^ ((row >> 1) & 7))) * 16); }
;     }
;     __builtin_amdgcn_s_setprio(1);
; #pragma unroll
;     for (int kc = 0; kc < 2; kc++)
; #pragma unroll
;       for (int m = 0; m < 4; m++)
; #pragma unroll
;         for (int n = 0; n < 4; n++) acc[m][n] = __builtin_amdgcn_mfma_f32_16x16x32_bf16(bfv[kc][n], af[kc][m], acc[m][n], 0, 0, 0);
;     __builtin_amdgcn_s_setprio(0);
;     asm volatile("s_waitcnt vmcnt(0) lgkmcnt(0)" ::: "memory"); __builtin_amdgcn_s_barrier(); asm volatile("" ::: "memory");
;   }
.LBB0_657:
	s_setprio 3
	s_and_b32 s28, s25, 0x8000
	s_xor_b32 s29, s28, 0x8000
	s_add_i32 s29, s29, vcc_hi
	s_mov_b32 m0, s29
	s_add_i32 vcc_lo, s29, 0x4000
	global_load_lds_dwordx4 v150, s[46:47]
	s_mov_b32 m0, vcc_lo
	s_add_i32 vcc_lo, s29, 0x1000
	global_load_lds_dwordx4 v151, s[46:47]
	s_mov_b32 m0, vcc_lo
	s_add_i32 vcc_lo, s29, 0x5000
	global_load_lds_dwordx4 v152, s[46:47]
	s_mov_b32 m0, vcc_lo
	s_add_i32 vcc_lo, s29, 0x2000
	global_load_lds_dwordx4 v153, s[46:47]
	s_mov_b32 m0, vcc_lo
	s_add_i32 vcc_lo, s29, 0x6000
	global_load_lds_dwordx4 v154, s[46:47]
	s_mov_b32 m0, vcc_lo
	s_add_i32 vcc_lo, s29, 0x3000
	global_load_lds_dwordx4 v155, s[46:47]
	s_mov_b32 m0, vcc_lo
	s_add_i32 vcc_lo, s29, 0x7000
	global_load_lds_dwordx4 v156, s[46:47]
	s_mov_b32 m0, vcc_lo
	s_nop 0
	global_load_lds_dwordx4 v157, s[46:47]
	v_add_u32_e32 v150, 0x80, v150
	v_add_u32_e32 v151, 0x80, v151
	v_add_u32_e32 v152, 0x80, v152
	v_add_u32_e32 v153, 0x80, v153
	v_add_u32_e32 v154, 0x80, v154
	v_add_u32_e32 v155, 0x80, v155
	v_add_u32_e32 v156, 0x80, v156
	v_add_u32_e32 v157, 0x80, v157
	v_add_u32_e32 v98, s28, v85
	v_add_u32_e32 v114, s28, v84
	v_add_u32_e32 v130, s28, v83
	v_add_u32_e32 v146, s28, v2
	ds_read_b128 v[86:89], v98
	ds_read_b128 v[90:93], v98 offset:2048
	ds_read_b128 v[94:97], v98 offset:4096
	ds_read_b128 v[98:101], v98 offset:6144
	ds_read_b128 v[102:105], v114 offset:16384
	ds_read_b128 v[106:109], v114 offset:18432
	ds_read_b128 v[110:113], v114 offset:20480
	ds_read_b128 v[114:117], v114 offset:22528
	ds_read_b128 v[118:121], v130
	ds_read_b128 v[122:125], v130 offset:2048
	ds_read_b128 v[126:129], v130 offset:4096
	ds_read_b128 v[130:133], v130 offset:6144
	ds_read_b128 v[134:137], v146 offset:16384
	ds_read_b128 v[138:141], v146 offset:18432
	ds_read_b128 v[142:145], v146 offset:20480
	ds_read_b128 v[146:149], v146 offset:22528
	s_setprio 1
	s_waitcnt lgkmcnt(0)
	v_mfma_f32_16x16x32_bf16 v[64:67], v[102:105], v[86:89], v[64:67]
	v_mfma_f32_16x16x32_bf16 v[60:63], v[106:109], v[86:89], v[60:63]
	v_mfma_f32_16x16x32_bf16 v[56:59], v[110:113], v[86:89], v[56:59]
	v_mfma_f32_16x16x32_bf16 v[52:55], v[114:117], v[86:89], v[52:55]
	v_mfma_f32_16x16x32_bf16 v[48:51], v[102:105], v[90:93], v[48:51]
	v_mfma_f32_16x16x32_bf16 v[44:47], v[106:109], v[90:93], v[44:47]
	v_mfma_f32_16x16x32_bf16 v[40:43], v[110:113], v[90:93], v[40:43]
	v_mfma_f32_16x16x32_bf16 v[36:39], v[114:117], v[90:93], v[36:39]
	v_mfma_f32_16x16x32_bf16 v[32:35], v[102:105], v[94:97], v[32:35]
	v_mfma_f32_16x16x32_bf16 v[28:31], v[106:109], v[94:97], v[28:31]
	v_mfma_f32_16x16x32_bf16 v[24:27], v[110:113], v[94:97], v[24:27]
	v_mfma_f32_16x16x32_bf16 v[20:23], v[114:117], v[94:97], v[20:23]
	v_mfma_f32_16x16x32_bf16 v[16:19], v[102:105], v[98:101], v[16:19]
	v_mfma_f32_16x16x32_bf16 v[12:15], v[106:109], v[98:101], v[12:15]
	v_mfma_f32_16x16x32_bf16 v[8:11], v[110:113], v[98:101], v[8:11]
	v_mfma_f32_16x16x32_bf16 v[4:7], v[114:117], v[98:101], v[4:7]
	v_mfma_f32_16x16x32_bf16 v[64:67], v[134:137], v[118:121], v[64:67]
	v_mfma_f32_16x16x32_bf16 v[60:63], v[138:141], v[118:121], v[60:63]
	v_mfma_f32_16x16x32_bf16 v[56:59], v[142:145], v[118:121], v[56:59]
	v_mfma_f32_16x16x32_bf16 v[52:55], v[146:149], v[118:121], v[52:55]
	v_mfma_f32_16x16x32_bf16 v[48:51], v[134:137], v[122:125], v[48:51]
	v_mfma_f32_16x16x32_bf16 v[44:47], v[138:141], v[122:125], v[44:47]
	v_mfma_f32_16x16x32_bf16 v[40:43], v[142:145], v[122:125], v[40:43]
	v_mfma_f32_16x16x32_bf16 v[36:39], v[146:149], v[122:125], v[36:39]
	v_mfma_f32_16x16x32_bf16 v[32:35], v[134:137], v[126:129], v[32:35]
	v_mfma_f32_16x16x32_bf16 v[28:31], v[138:141], v[126:129], v[28:31]
	v_mfma_f32_16x16x32_bf16 v[24:27], v[142:145], v[126:129], v[24:27]
	v_mfma_f32_16x16x32_bf16 v[20:23], v[146:149], v[126:129], v[20:23]
	v_mfma_f32_16x16x32_bf16 v[16:19], v[134:137], v[130:133], v[16:19]
	v_mfma_f32_16x16x32_bf16 v[12:15], v[138:141], v[130:133], v[12:15]
	v_mfma_f32_16x16x32_bf16 v[8:11], v[142:145], v[130:133], v[8:11]
	v_mfma_f32_16x16x32_bf16 v[4:7], v[146:149], v[130:133], v[4:7]
	s_setprio 0
	s_waitcnt vmcnt(0) lgkmcnt(0)
	s_barrier
	s_add_u32 s26, s26, 0x80
	s_addc_u32 s27, s27, 0
	s_add_i32 s25, s25, 0x8000
	s_cmpk_eq_i32 s26, 0x780
	s_cbranch_scc0 .LBB0_657
; __device__ __forceinline__ unsigned pk2(float lo, float hi) { unsigned r; asm("v_cvt_pk_bf16_f32 %0, %1, %2" : "=v"(r) : "v"(lo), "v"(hi)); return r; }
; __device__ __forceinline__ float bflo(unsigned u) { return __uint_as_float(u << 16); }
; __device__ __forceinline__ float bfhi(unsigned u) { return __uint_as_float(u & 0xffff0000u); }
; __device__ __forceinline__ void gemm_mainloop_d(const bf16_t* __restrict__ Ap, int lda, const bf16_t* __restrict__ Bt, int K,
;                                                 int m0, int n0, f32x4 (&acc)[4][4], char* lds) {
;     ...
;     const char* la = lds + st * 32768; const char* lb = la + 16384;
;     bf16x8 af[2][4], bfv[2][4];
; #pragma unroll
;     for (int kc = 0; kc < 2; kc++) {
; #pragma unroll
;       for (int m = 0; m < 4; m++) { const int row = wr * 64 + m * 16 + fr; af[kc][m] = *(const bf16x8*)(la + (row * 8 + ((kc * 4 + fq) ^ ((row >> 1) & 7))) * 16); }
; #pragma unroll
;       for (int n = 0; n < 4; n++) { const int row = wc * 64 + n * 16 + fr; bfv[kc][n] = *(const bf16x8*)(lb + (row * 8 + ((kc * 4 + fq) ^ ((row >> 1) & 7))) * 16); }
;     }
;     __builtin_amdgcn_s_setprio(1);
; #pragma unroll
;     for (int kc = 0; kc < 2; kc++)
; #pragma unroll
;       for (int m = 0; m < 4; m++)
; #pragma unroll
;         for (int n = 0; n < 4; n++) acc[m][n] = __builtin_amdgcn_mfma_f32_16x16x32_bf16(bfv[kc][n], af[kc][m], acc[m][n], 0, 0, 0);
;     __builtin_amdgcn_s_setprio(0);
;     asm volatile("s_waitcnt vmcnt(0) lgkmcnt(0)" ::: "memory"); __builtin_amdgcn_s_barrier(); asm volatile("" ::: "memory");
; __device__ __forceinline__ void gemm_A(const Params& p, int item, char* lds) {
;     ...
; #pragma unroll
;   for (int m = 0; m < 4; m++) {
;     const int rl = wr * 64 + m * 16 + fr; const float r = rsqrtf(rssg[rl] * (1.f / 1024.f) + 1e-6f);
;     float sq = 0.f;
; #pragma unroll
;     for (int n = 0; n < 4; n++) {
;       const int col = n0 + wc * 64 + n * 16 + fq * 4;
;       if (col < PIN) { f32x4 v = acc[m][n] * r; u32x2 w; w[0] = pk2(v[0], v[1]); w[1] = pk2(v[2], v[3]); *(u32x2*)(P + (size_t)(m0 + rl) * PIN + col) = w;
;         const float b0 = bflo(w[0]), b1 = bfhi(w[0]), b2 = bflo(w[1]), b3 = bfhi(w[1]); sq += b0 * b0 + b1 * b1 + b2 * b2 + b3 * b3; }
	v_add_u32_e32 v0, 0, v85
	ds_read_b128 v[68:71], v0 offset:32768
	ds_read_b128 v[72:75], v0 offset:34816
	ds_read_b128 v[76:79], v0 offset:36864
	ds_read_b128 v[86:89], v0 offset:38912
	v_add_u32_e32 v0, 0, v84
	ds_read_b128 v[90:93], v0 offset:49152
	ds_read_b128 v[94:97], v0 offset:51200
	ds_read_b128 v[98:101], v0 offset:53248
	ds_read_b128 v[102:105], v0 offset:55296
	v_add_u32_e32 v0, 0, v83
	ds_read_b128 v[80:83], v0 offset:32768
	ds_read_b128 v[106:109], v0 offset:34816
	ds_read_b128 v[110:113], v0 offset:36864
	ds_read_b128 v[114:117], v0 offset:38912
	v_add_u32_e32 v0, 0, v2
	ds_read_b128 v[118:121], v0 offset:49152
	ds_read_b128 v[122:125], v0 offset:51200
	ds_read_b128 v[126:129], v0 offset:53248
	ds_read_b128 v[130:133], v0 offset:55296
	s_setprio 1
	s_waitcnt lgkmcnt(0)
	v_mfma_f32_16x16x32_bf16 v[64:67], v[90:93], v[68:71], v[64:67]
	v_mfma_f32_16x16x32_bf16 v[60:63], v[94:97], v[68:71], v[60:63]
	v_mfma_f32_16x16x32_bf16 v[56:59], v[98:101], v[68:71], v[56:59]
	v_mfma_f32_16x16x32_bf16 v[52:55], v[102:105], v[68:71], v[52:55]
	v_mfma_f32_16x16x32_bf16 v[48:51], v[90:93], v[72:75], v[48:51]
	v_mfma_f32_16x16x32_bf16 v[44:47], v[94:97], v[72:75], v[44:47]
	v_mfma_f32_16x16x32_bf16 v[40:43], v[98:101], v[72:75], v[40:43]
	v_mfma_f32_16x16x32_bf16 v[36:39], v[102:105], v[72:75], v[36:39]
	v_mfma_f32_16x16x32_bf16 v[32:35], v[90:93], v[76:79], v[32:35]
	v_mfma_f32_16x16x32_bf16 v[28:31], v[94:97], v[76:79], v[28:31]
	v_mfma_f32_16x16x32_bf16 v[24:27], v[98:101], v[76:79], v[24:27]
	v_mfma_f32_16x16x32_bf16 v[20:23], v[102:105], v[76:79], v[20:23]
	v_mfma_f32_16x16x32_bf16 v[16:19], v[90:93], v[86:89], v[16:19]
	v_mfma_f32_16x16x32_bf16 v[12:15], v[94:97], v[86:89], v[12:15]
	v_mfma_f32_16x16x32_bf16 v[8:11], v[98:101], v[86:89], v[8:11]
	v_mfma_f32_16x16x32_bf16 v[4:7], v[102:105], v[86:89], v[4:7]
	v_mfma_f32_16x16x32_bf16 v[64:67], v[118:121], v[80:83], v[64:67]
	v_mfma_f32_16x16x32_bf16 v[60:63], v[122:125], v[80:83], v[60:63]
	v_mfma_f32_16x16x32_bf16 v[56:59], v[126:129], v[80:83], v[56:59]
	v_mfma_f32_16x16x32_bf16 v[52:55], v[130:133], v[80:83], v[52:55]
	v_mfma_f32_16x16x32_bf16 v[48:51], v[118:121], v[106:109], v[48:51]
	v_mfma_f32_16x16x32_bf16 v[44:47], v[122:125], v[106:109], v[44:47]
	v_mfma_f32_16x16x32_bf16 v[40:43], v[126:129], v[106:109], v[40:43]
	v_mfma_f32_16x16x32_bf16 v[36:39], v[130:133], v[106:109], v[36:39]
	v_mfma_f32_16x16x32_bf16 v[32:35], v[118:121], v[110:113], v[32:35]
	v_mfma_f32_16x16x32_bf16 v[28:31], v[122:125], v[110:113], v[28:31]
	v_mfma_f32_16x16x32_bf16 v[24:27], v[126:129], v[110:113], v[24:27]
	v_mfma_f32_16x16x32_bf16 v[20:23], v[130:133], v[110:113], v[20:23]
	v_mfma_f32_16x16x32_bf16 v[16:19], v[118:121], v[114:117], v[16:19]
	v_mfma_f32_16x16x32_bf16 v[12:15], v[122:125], v[114:117], v[12:15]
	v_mfma_f32_16x16x32_bf16 v[8:11], v[126:129], v[114:117], v[8:11]
	v_mfma_f32_16x16x32_bf16 v[4:7], v[130:133], v[114:117], v[4:7]
	s_setprio 0
	v_mov_b32_e32 v2, v198
	s_mov_b32 s25, s89
	s_waitcnt vmcnt(0) lgkmcnt(0)
	s_add_u32 s28, s46, s25
	s_addc_u32 s29, s47, 0
	s_ashr_i32 s25, s24, 31
	v_and_b32_e32 v0, 15, v2
	s_lshl_b64 s[26:27], s[24:25], 2
	v_ashrrev_i32_e32 v1, 1, v2
	s_movk_i32 s4, 0xffc0
	s_add_u32 s28, s28, s26
	v_and_or_b32 v0, v1, s4, v0
	s_addc_u32 s29, s29, s27
	v_ashrrev_i32_e32 v1, 31, v0
	v_lshl_add_u64 v[70:71], v[0:1], 2, s[28:29]
	s_mov_b32 s28, 0xff8c000
	v_add_co_u32_e32 v68, vcc, s28, v70
	s_mov_b32 s25, s89
	s_nop 0
	v_addc_co_u32_e32 v69, vcc, 0, v71, vcc
	global_load_dword v69, v[68:69], off
	v_and_b32_e32 v68, 64, v2
	v_bfe_u32 v2, v2, 4, 2
	v_lshlrev_b32_e32 v72, 2, v2
	v_or3_b32 v68, v72, v68, s3
	s_add_u32 s3, s46, s25
	s_addc_u32 s25, s47, 0
	s_add_u32 s30, s3, 0x768000
	s_addc_u32 s31, s25, 0
	v_add_u32_e32 v74, s24, v0
	v_mov_b32_e32 v76, 0
	v_cmp_gt_i32_e64 s[34:35], s78, v68
	s_waitcnt vmcnt(0)
	v_fmamk_f32 v69, v69, 0x3a800000, v200
	v_mul_f32_e32 v72, 0x4b800000, v69
	v_cmp_gt_f32_e32 vcc, s83, v69
	s_nop 1
	v_cndmask_b32_e32 v69, v69, v72, vcc
	v_rsq_f32_e32 v69, v69
	v_mov_b64_e32 v[72:73], s[30:31]
	v_mad_i64_i32 v[72:73], s[28:29], v74, s69, v[72:73]
	v_mul_f32_e32 v74, 0x45800000, v69
	v_cndmask_b32_e32 v74, v69, v74, vcc
	v_mov_b32_e32 v75, v74
	v_ashrrev_i32_e32 v69, 31, v68
	s_and_saveexec_b64 s[28:29], s[34:35]
	s_cbranch_execz .LBB0_660
	v_mov_b32_e32 v76, v74
	v_mov_b32_e32 v77, v74
	v_pk_mul_f32 v[66:67], v[66:67], v[76:77]
	v_pk_mul_f32 v[64:65], v[64:65], v[74:75]
	s_nop 0
	v_cvt_pk_bf16_f32 v64, v64, v65
	v_cvt_pk_bf16_f32 v65, v66, v67
	v_lshl_add_u64 v[66:67], v[68:69], 1, v[72:73]
	global_store_dwordx2 v[66:67], v[64:65], off
	v_lshlrev_b32_e32 v66, 16, v64
	v_and_b32_e32 v67, 0xffff0000, v64
	v_pk_mul_f32 v[66:67], v[66:67], v[66:67]
	v_and_b32_e32 v64, 0xffff0000, v65
	v_lshlrev_b32_e32 v65, 16, v65
	v_pk_mul_f32 v[64:65], v[64:65], v[64:65]
	v_add_f32_e32 v66, v66, v67
	v_add_f32_e32 v65, v66, v65
	v_add_f32_e32 v76, v64, v65
